# inverted GEMM K-loop priorities + activation-tile DMA pieces first
# baseline (speedup 1.0000x reference)
.Lskw_P1:
	s_waitcnt lgkmcnt(0)
	s_barrier
	s_setprio 0
	s_waitcnt lgkmcnt(0)
	v_mfma_f32_16x16x32_bf16 v[124:127], v[148:151], v[186:189], v[124:127]
	v_mfma_f32_16x16x32_bf16 v[120:123], v[156:159], v[186:189], v[120:123]
	v_mfma_f32_16x16x32_bf16 v[108:111], v[148:151], v[194:197], v[108:111]
	v_mfma_f32_16x16x32_bf16 v[104:107], v[156:159], v[194:197], v[104:107]
	v_mfma_f32_16x16x32_bf16 v[92:95], v[148:151], v[202:205], v[92:95]
	v_mfma_f32_16x16x32_bf16 v[88:91], v[156:159], v[202:205], v[88:91]
	v_mfma_f32_16x16x32_bf16 v[76:79], v[148:151], v[210:213], v[76:79]
	v_mfma_f32_16x16x32_bf16 v[72:75], v[156:159], v[210:213], v[72:75]
	v_mfma_f32_16x16x32_bf16 v[124:127], v[152:155], v[190:193], v[124:127]
	v_mfma_f32_16x16x32_bf16 v[120:123], v[160:163], v[190:193], v[120:123]
	v_mfma_f32_16x16x32_bf16 v[108:111], v[152:155], v[198:201], v[108:111]
	v_mfma_f32_16x16x32_bf16 v[104:107], v[160:163], v[198:201], v[104:107]
	v_mfma_f32_16x16x32_bf16 v[92:95], v[152:155], v[206:209], v[92:95]
	v_mfma_f32_16x16x32_bf16 v[88:91], v[160:163], v[206:209], v[88:91]
	v_mfma_f32_16x16x32_bf16 v[76:79], v[152:155], v[214:217], v[76:79]
	v_mfma_f32_16x16x32_bf16 v[72:75], v[160:163], v[214:217], v[72:75]
	s_setprio 1
	s_setprio 0
	v_mfma_f32_16x16x32_bf16 v[116:119], v[164:167], v[186:189], v[116:119]
	v_mfma_f32_16x16x32_bf16 v[112:115], v[178:181], v[186:189], v[112:115]
	v_mfma_f32_16x16x32_bf16 v[100:103], v[164:167], v[194:197], v[100:103]
	v_mfma_f32_16x16x32_bf16 v[96:99], v[178:181], v[194:197], v[96:99]
	v_mfma_f32_16x16x32_bf16 v[84:87], v[164:167], v[202:205], v[84:87]
	v_mfma_f32_16x16x32_bf16 v[80:83], v[178:181], v[202:205], v[80:83]
	v_mfma_f32_16x16x32_bf16 v[68:71], v[164:167], v[210:213], v[68:71]
	v_mfma_f32_16x16x32_bf16 v[64:67], v[178:181], v[210:213], v[64:67]
	v_mfma_f32_16x16x32_bf16 v[116:119], v[168:171], v[190:193], v[116:119]
	v_mfma_f32_16x16x32_bf16 v[112:115], v[182:185], v[190:193], v[112:115]
	v_mfma_f32_16x16x32_bf16 v[100:103], v[168:171], v[198:201], v[100:103]
	v_mfma_f32_16x16x32_bf16 v[96:99], v[182:185], v[198:201], v[96:99]
	v_mfma_f32_16x16x32_bf16 v[84:87], v[168:171], v[206:209], v[84:87]
	v_mfma_f32_16x16x32_bf16 v[80:83], v[182:185], v[206:209], v[80:83]
	v_mfma_f32_16x16x32_bf16 v[68:71], v[168:171], v[214:217], v[68:71]
	v_mfma_f32_16x16x32_bf16 v[64:67], v[182:185], v[214:217], v[64:67]
	s_setprio 1
	s_barrier
	v_lshl_add_u64 v[252:253], s[46:47], 0, v[128:129]
	s_mov_b32 m0, s51
	s_nop 0
	global_load_lds_dwordx4 v[252:253], off
	v_lshl_add_u64 v[252:253], s[46:47], 0, v[132:133]
	s_mov_b32 m0, s52
	s_nop 0
	global_load_lds_dwordx4 v[252:253], off
	s_add_i32 s27, s64, s50
	v_lshl_add_u64 v[218:219], s[44:45], 0, v[130:131]
	s_mov_b32 m0, s27
	ds_read_b128 v[186:189], v177 offset:16384
	ds_read_b128 v[190:193], v177 offset:17408
	ds_read_b128 v[194:197], v177 offset:18432
	ds_read_b128 v[198:201], v177 offset:19456
	ds_read_b128 v[202:205], v177 offset:20480
	ds_read_b128 v[206:209], v177 offset:21504
	ds_read_b128 v[210:213], v177 offset:22528
	ds_read_b128 v[214:217], v177 offset:23552
	global_load_lds_dwordx4 v[218:219], off
	s_add_i32 m0, s27, 0x2000
	s_add_u32 s34, s44, 0x40000
	v_lshl_add_u64 v[220:221], s[44:45], 0, v[134:135]
	s_addc_u32 s35, s45, 0
	s_add_i32 s27, s65, s50
	global_load_lds_dwordx4 v[220:221], off
	v_lshl_add_u64 v[222:223], s[34:35], 0, v[130:131]
	s_mov_b32 m0, s27
	v_lshl_add_u64 v[224:225], s[46:47], 0, v[132:133]
	global_load_lds_dwordx4 v[222:223], off
	v_lshl_add_u64 v[222:223], s[34:35], 0, v[134:135]
	s_add_i32 m0, s27, 0x2000
	s_nop 0
	global_load_lds_dwordx4 v[222:223], off
	v_lshl_add_u64 v[222:223], s[46:47], 0, v[128:129]
	s_waitcnt vmcnt(8)
	s_waitcnt lgkmcnt(0)
	s_barrier
	s_setprio 0
	s_waitcnt lgkmcnt(0)
	v_mfma_f32_16x16x32_bf16 v[60:63], v[148:151], v[186:189], v[60:63]
	v_mfma_f32_16x16x32_bf16 v[56:59], v[156:159], v[186:189], v[56:59]
	v_mfma_f32_16x16x32_bf16 v[44:47], v[148:151], v[194:197], v[44:47]
	v_mfma_f32_16x16x32_bf16 v[40:43], v[156:159], v[194:197], v[40:43]
	v_mfma_f32_16x16x32_bf16 v[28:31], v[148:151], v[202:205], v[28:31]
	v_mfma_f32_16x16x32_bf16 v[24:27], v[156:159], v[202:205], v[24:27]
	v_mfma_f32_16x16x32_bf16 v[12:15], v[148:151], v[210:213], v[12:15]
	v_mfma_f32_16x16x32_bf16 v[8:11], v[156:159], v[210:213], v[8:11]
	v_mfma_f32_16x16x32_bf16 v[60:63], v[152:155], v[190:193], v[60:63]
	v_mfma_f32_16x16x32_bf16 v[56:59], v[160:163], v[190:193], v[56:59]
	v_mfma_f32_16x16x32_bf16 v[44:47], v[152:155], v[198:201], v[44:47]
	v_mfma_f32_16x16x32_bf16 v[40:43], v[160:163], v[198:201], v[40:43]
	v_mfma_f32_16x16x32_bf16 v[28:31], v[152:155], v[206:209], v[28:31]
	v_mfma_f32_16x16x32_bf16 v[24:27], v[160:163], v[206:209], v[24:27]
	v_mfma_f32_16x16x32_bf16 v[12:15], v[152:155], v[214:217], v[12:15]
	v_mfma_f32_16x16x32_bf16 v[8:11], v[160:163], v[214:217], v[8:11]
	s_setprio 1
	s_setprio 0
	v_mfma_f32_16x16x32_bf16 v[52:55], v[164:167], v[186:189], v[52:55]
	v_mfma_f32_16x16x32_bf16 v[48:51], v[178:181], v[186:189], v[48:51]
	v_mfma_f32_16x16x32_bf16 v[36:39], v[164:167], v[194:197], v[36:39]
	v_mfma_f32_16x16x32_bf16 v[32:35], v[178:181], v[194:197], v[32:35]
	v_mfma_f32_16x16x32_bf16 v[20:23], v[164:167], v[202:205], v[20:23]
	v_mfma_f32_16x16x32_bf16 v[16:19], v[178:181], v[202:205], v[16:19]
	v_mfma_f32_16x16x32_bf16 v[4:7], v[164:167], v[210:213], v[4:7]
	v_mfma_f32_16x16x32_bf16 v[0:3], v[178:181], v[210:213], v[0:3]
	v_mfma_f32_16x16x32_bf16 v[52:55], v[168:171], v[190:193], v[52:55]
	v_mfma_f32_16x16x32_bf16 v[48:51], v[182:185], v[190:193], v[48:51]
	v_mfma_f32_16x16x32_bf16 v[36:39], v[168:171], v[198:201], v[36:39]
	v_mfma_f32_16x16x32_bf16 v[32:35], v[182:185], v[198:201], v[32:35]
	v_mfma_f32_16x16x32_bf16 v[20:23], v[168:171], v[206:209], v[20:23]
	v_mfma_f32_16x16x32_bf16 v[16:19], v[182:185], v[206:209], v[16:19]
	v_mfma_f32_16x16x32_bf16 v[4:7], v[168:171], v[214:217], v[4:7]
	v_mfma_f32_16x16x32_bf16 v[0:3], v[182:185], v[214:217], v[0:3]
	s_setprio 1
	s_barrier
	s_add_i32 s27, 0, 0x18000
	v_add_u32_e32 v136, s27, v173
	s_add_i32 s30, 0, 0x1c000
	ds_read_b128 v[148:151], v136
	ds_read_b128 v[152:155], v136 offset:1024
	ds_read_b128 v[156:159], v136 offset:2048
	ds_read_b128 v[160:163], v136 offset:3072
	v_add_u32_e32 v136, s30, v173
	ds_read_b128 v[164:167], v136
	ds_read_b128 v[168:171], v136 offset:1024
	ds_read_b128 v[178:181], v136 offset:2048
	ds_read_b128 v[182:185], v136 offset:3072
	s_add_u32 s34, s46, 0x40000
	s_addc_u32 s35, s47, 0
	s_mov_b32 m0, s53
	v_lshl_add_u64 v[226:227], s[34:35], 0, v[128:129]
	ds_read_b128 v[186:189], v177 offset:32768
	ds_read_b128 v[190:193], v177 offset:33792
	ds_read_b128 v[194:197], v177 offset:34816
	ds_read_b128 v[198:201], v177 offset:35840
	ds_read_b128 v[202:205], v177 offset:36864
	ds_read_b128 v[206:209], v177 offset:37888
	ds_read_b128 v[210:213], v177 offset:38912
	ds_read_b128 v[214:217], v177 offset:39936
	global_load_lds_dwordx4 v[226:227], off
	v_lshl_add_u64 v[226:227], s[34:35], 0, v[132:133]
	s_mov_b32 m0, s54
	s_nop 0
	global_load_lds_dwordx4 v[226:227], off
	s_waitcnt vmcnt(8)
	s_waitcnt lgkmcnt(0)
	s_barrier
	s_setprio 0
	s_waitcnt lgkmcnt(0)
	v_mfma_f32_16x16x32_bf16 v[124:127], v[148:151], v[186:189], v[124:127]
	v_mfma_f32_16x16x32_bf16 v[120:123], v[156:159], v[186:189], v[120:123]
	v_mfma_f32_16x16x32_bf16 v[108:111], v[148:151], v[194:197], v[108:111]
	v_mfma_f32_16x16x32_bf16 v[104:107], v[156:159], v[194:197], v[104:107]
	v_mfma_f32_16x16x32_bf16 v[92:95], v[148:151], v[202:205], v[92:95]
	v_mfma_f32_16x16x32_bf16 v[88:91], v[156:159], v[202:205], v[88:91]
	v_mfma_f32_16x16x32_bf16 v[76:79], v[148:151], v[210:213], v[76:79]
	v_mfma_f32_16x16x32_bf16 v[72:75], v[156:159], v[210:213], v[72:75]
	v_mfma_f32_16x16x32_bf16 v[124:127], v[152:155], v[190:193], v[124:127]
	v_mfma_f32_16x16x32_bf16 v[120:123], v[160:163], v[190:193], v[120:123]
	v_mfma_f32_16x16x32_bf16 v[108:111], v[152:155], v[198:201], v[108:111]
	v_mfma_f32_16x16x32_bf16 v[104:107], v[160:163], v[198:201], v[104:107]
	v_mfma_f32_16x16x32_bf16 v[92:95], v[152:155], v[206:209], v[92:95]
	v_mfma_f32_16x16x32_bf16 v[88:91], v[160:163], v[206:209], v[88:91]
	v_mfma_f32_16x16x32_bf16 v[76:79], v[152:155], v[214:217], v[76:79]
	v_mfma_f32_16x16x32_bf16 v[72:75], v[160:163], v[214:217], v[72:75]
	s_setprio 1
	s_setprio 0
	v_mfma_f32_16x16x32_bf16 v[116:119], v[164:167], v[186:189], v[116:119]
	v_mfma_f32_16x16x32_bf16 v[112:115], v[178:181], v[186:189], v[112:115]
	v_mfma_f32_16x16x32_bf16 v[100:103], v[164:167], v[194:197], v[100:103]
	v_mfma_f32_16x16x32_bf16 v[96:99], v[178:181], v[194:197], v[96:99]
	v_mfma_f32_16x16x32_bf16 v[84:87], v[164:167], v[202:205], v[84:87]
	v_mfma_f32_16x16x32_bf16 v[80:83], v[178:181], v[202:205], v[80:83]
	v_mfma_f32_16x16x32_bf16 v[68:71], v[164:167], v[210:213], v[68:71]
	v_mfma_f32_16x16x32_bf16 v[64:67], v[178:181], v[210:213], v[64:67]
	v_mfma_f32_16x16x32_bf16 v[116:119], v[168:171], v[190:193], v[116:119]
	v_mfma_f32_16x16x32_bf16 v[112:115], v[182:185], v[190:193], v[112:115]
	v_mfma_f32_16x16x32_bf16 v[100:103], v[168:171], v[198:201], v[100:103]
	v_mfma_f32_16x16x32_bf16 v[96:99], v[182:185], v[198:201], v[96:99]
	v_mfma_f32_16x16x32_bf16 v[84:87], v[168:171], v[206:209], v[84:87]
	v_mfma_f32_16x16x32_bf16 v[80:83], v[182:185], v[206:209], v[80:83]
	v_mfma_f32_16x16x32_bf16 v[68:71], v[168:171], v[214:217], v[68:71]
	v_mfma_f32_16x16x32_bf16 v[64:67], v[182:185], v[214:217], v[64:67]
	s_setprio 1
	s_barrier
	v_lshl_add_u64 v[252:253], v[222:223], 0, s[20:21]
	s_mov_b32 m0, s62
	s_nop 0
	global_load_lds_dwordx4 v[252:253], off
	v_lshl_add_u64 v[252:253], v[224:225], 0, s[20:21]
	s_mov_b32 m0, s63
	s_nop 0
	global_load_lds_dwordx4 v[252:253], off
	s_add_i32 s27, s27, s50
	v_lshl_add_u64 v[218:219], v[218:219], 0, s[20:21]
	s_mov_b32 m0, s27
	ds_read_b128 v[186:189], v177 offset:49152
	ds_read_b128 v[190:193], v177 offset:50176
	ds_read_b128 v[194:197], v177 offset:51200
	ds_read_b128 v[198:201], v177 offset:52224
	ds_read_b128 v[202:205], v177 offset:53248
	ds_read_b128 v[206:209], v177 offset:54272
	ds_read_b128 v[210:213], v177 offset:55296
	ds_read_b128 v[214:217], v177 offset:56320
	global_load_lds_dwordx4 v[218:219], off
	s_add_i32 m0, s27, 0x2000
	s_add_u32 s34, s44, 0x40080
	v_lshl_add_u64 v[218:219], v[220:221], 0, s[20:21]
	s_addc_u32 s35, s45, 0
	s_add_i32 s27, s30, s50
	global_load_lds_dwordx4 v[218:219], off
	v_lshl_add_u64 v[218:219], s[34:35], 0, v[130:131]
	s_mov_b32 m0, s27
	s_nop 0
	global_load_lds_dwordx4 v[218:219], off
	v_lshl_add_u64 v[218:219], s[34:35], 0, v[134:135]
	s_add_i32 m0, s27, 0x2000
	s_nop 0
	global_load_lds_dwordx4 v[218:219], off
	v_lshl_add_u64 v[218:219], v[222:223], 0, s[20:21]
	v_lshl_add_u64 v[218:219], v[224:225], 0, s[20:21]
	s_waitcnt vmcnt(8)
	s_waitcnt lgkmcnt(0)
	s_barrier
	s_setprio 0
	s_waitcnt lgkmcnt(0)
	v_mfma_f32_16x16x32_bf16 v[60:63], v[148:151], v[186:189], v[60:63]
	v_mfma_f32_16x16x32_bf16 v[56:59], v[156:159], v[186:189], v[56:59]
	v_mfma_f32_16x16x32_bf16 v[44:47], v[148:151], v[194:197], v[44:47]
	v_mfma_f32_16x16x32_bf16 v[40:43], v[156:159], v[194:197], v[40:43]
	v_mfma_f32_16x16x32_bf16 v[28:31], v[148:151], v[202:205], v[28:31]
	v_mfma_f32_16x16x32_bf16 v[24:27], v[156:159], v[202:205], v[24:27]
	v_mfma_f32_16x16x32_bf16 v[12:15], v[148:151], v[210:213], v[12:15]
	v_mfma_f32_16x16x32_bf16 v[8:11], v[156:159], v[210:213], v[8:11]
	v_mfma_f32_16x16x32_bf16 v[60:63], v[152:155], v[190:193], v[60:63]
	v_mfma_f32_16x16x32_bf16 v[56:59], v[160:163], v[190:193], v[56:59]
	v_mfma_f32_16x16x32_bf16 v[44:47], v[152:155], v[198:201], v[44:47]
	v_mfma_f32_16x16x32_bf16 v[40:43], v[160:163], v[198:201], v[40:43]
	v_mfma_f32_16x16x32_bf16 v[28:31], v[152:155], v[206:209], v[28:31]
	v_mfma_f32_16x16x32_bf16 v[24:27], v[160:163], v[206:209], v[24:27]
	v_mfma_f32_16x16x32_bf16 v[12:15], v[152:155], v[214:217], v[12:15]
	v_mfma_f32_16x16x32_bf16 v[8:11], v[160:163], v[214:217], v[8:11]
	s_setprio 1
	s_setprio 0
	v_mfma_f32_16x16x32_bf16 v[52:55], v[164:167], v[186:189], v[52:55]
	v_mfma_f32_16x16x32_bf16 v[48:51], v[178:181], v[186:189], v[48:51]
	v_mfma_f32_16x16x32_bf16 v[36:39], v[164:167], v[194:197], v[36:39]
	v_mfma_f32_16x16x32_bf16 v[32:35], v[178:181], v[194:197], v[32:35]
	v_mfma_f32_16x16x32_bf16 v[20:23], v[164:167], v[202:205], v[20:23]
	v_mfma_f32_16x16x32_bf16 v[16:19], v[178:181], v[202:205], v[16:19]
	v_mfma_f32_16x16x32_bf16 v[4:7], v[164:167], v[210:213], v[4:7]
	v_mfma_f32_16x16x32_bf16 v[0:3], v[178:181], v[210:213], v[0:3]
	v_mfma_f32_16x16x32_bf16 v[52:55], v[168:171], v[190:193], v[52:55]
	v_mfma_f32_16x16x32_bf16 v[48:51], v[182:185], v[190:193], v[48:51]
	v_mfma_f32_16x16x32_bf16 v[36:39], v[168:171], v[198:201], v[36:39]
	v_mfma_f32_16x16x32_bf16 v[32:35], v[182:185], v[198:201], v[32:35]
	v_mfma_f32_16x16x32_bf16 v[20:23], v[168:171], v[206:209], v[20:23]
	v_mfma_f32_16x16x32_bf16 v[16:19], v[182:185], v[206:209], v[16:19]
	v_mfma_f32_16x16x32_bf16 v[4:7], v[168:171], v[214:217], v[4:7]
	v_mfma_f32_16x16x32_bf16 v[0:3], v[182:185], v[214:217], v[0:3]
	s_setprio 1
	s_barrier
	s_add_i32 s25, s25, 2
	s_add_u32 s42, s42, 0x100
	s_addc_u32 s43, s43, 0
	s_add_u32 s23, s23, 0x100
	s_addc_u32 s24, s24, 0
	s_cmp_gt_u32 s25, 13
	s_cbranch_scc0 .LBB5_248
	s_nop 0
	s_nop 0
	s_nop 0
	s_nop 0
	s_nop 0
	s_nop 0
	s_nop 0
	s_nop 0
	s_setprio 0
	s_nop 0
	s_nop 0
	s_nop 0
	s_nop 0
	s_nop 0
	s_nop 0
	s_nop 0
	s_nop 0
	s_nop 0
	s_nop 0
	s_nop 0
	s_nop 0
	s_nop 0
	s_and_b64 vcc, exec, s[18:19]
	s_cbranch_vccz .LBB5_251
	s_barrier

.Lskw_P3:
	s_waitcnt lgkmcnt(0)
	s_barrier
	s_setprio 0
	s_waitcnt lgkmcnt(0)
	v_mfma_f32_16x16x32_bf16 v[156:159], v[64:67], v[160:163], v[156:159]
	v_mfma_f32_16x16x32_bf16 v[152:155], v[72:75], v[160:163], v[152:155]
	v_mfma_f32_16x16x32_bf16 v[124:127], v[64:67], v[168:171], v[124:127]
	v_mfma_f32_16x16x32_bf16 v[120:123], v[72:75], v[168:171], v[120:123]
	v_mfma_f32_16x16x32_bf16 v[108:111], v[64:67], v[176:179], v[108:111]
	v_mfma_f32_16x16x32_bf16 v[104:107], v[72:75], v[176:179], v[104:107]
	v_mfma_f32_16x16x32_bf16 v[92:95], v[64:67], v[184:187], v[92:95]
	v_mfma_f32_16x16x32_bf16 v[88:91], v[72:75], v[184:187], v[88:91]
	v_mfma_f32_16x16x32_bf16 v[156:159], v[68:71], v[164:167], v[156:159]
	v_mfma_f32_16x16x32_bf16 v[152:155], v[76:79], v[164:167], v[152:155]
	v_mfma_f32_16x16x32_bf16 v[124:127], v[68:71], v[172:175], v[124:127]
	v_mfma_f32_16x16x32_bf16 v[120:123], v[76:79], v[172:175], v[120:123]
	v_mfma_f32_16x16x32_bf16 v[108:111], v[68:71], v[180:183], v[108:111]
	v_mfma_f32_16x16x32_bf16 v[104:107], v[76:79], v[180:183], v[104:107]
	v_mfma_f32_16x16x32_bf16 v[92:95], v[68:71], v[188:191], v[92:95]
	v_mfma_f32_16x16x32_bf16 v[88:91], v[76:79], v[188:191], v[88:91]
	s_setprio 1
	s_setprio 0
	v_mfma_f32_16x16x32_bf16 v[132:135], v[136:139], v[160:163], v[132:135]
	v_mfma_f32_16x16x32_bf16 v[128:131], v[144:147], v[160:163], v[128:131]
	v_mfma_f32_16x16x32_bf16 v[116:119], v[136:139], v[168:171], v[116:119]
	v_mfma_f32_16x16x32_bf16 v[112:115], v[144:147], v[168:171], v[112:115]
	v_mfma_f32_16x16x32_bf16 v[100:103], v[136:139], v[176:179], v[100:103]
	v_mfma_f32_16x16x32_bf16 v[96:99], v[144:147], v[176:179], v[96:99]
	v_mfma_f32_16x16x32_bf16 v[84:87], v[136:139], v[184:187], v[84:87]
	v_mfma_f32_16x16x32_bf16 v[80:83], v[144:147], v[184:187], v[80:83]
	v_mfma_f32_16x16x32_bf16 v[132:135], v[140:143], v[164:167], v[132:135]
	v_mfma_f32_16x16x32_bf16 v[128:131], v[148:151], v[164:167], v[128:131]
	v_mfma_f32_16x16x32_bf16 v[116:119], v[140:143], v[172:175], v[116:119]
	v_mfma_f32_16x16x32_bf16 v[112:115], v[148:151], v[172:175], v[112:115]
	v_mfma_f32_16x16x32_bf16 v[100:103], v[140:143], v[180:183], v[100:103]
	v_mfma_f32_16x16x32_bf16 v[96:99], v[148:151], v[180:183], v[96:99]
	v_mfma_f32_16x16x32_bf16 v[84:87], v[140:143], v[188:191], v[84:87]
	v_mfma_f32_16x16x32_bf16 v[80:83], v[148:151], v[188:191], v[80:83]
	s_setprio 1
	s_barrier
	v_lshl_add_u64 v[252:253], s[44:45], 0, v[200:201]
	s_mov_b32 m0, s39
	s_nop 0
	global_load_lds_dwordx4 v[252:253], off
	v_lshl_add_u64 v[252:253], s[44:45], 0, v[204:205]
	s_mov_b32 m0, s48
	s_nop 0
	global_load_lds_dwordx4 v[252:253], off
	s_add_i32 s35, s55, s46
	v_lshl_add_u64 v[192:193], s[42:43], 0, v[202:203]
	s_mov_b32 m0, s35
	ds_read_b128 v[160:163], v231 offset:16384
	ds_read_b128 v[164:167], v231 offset:17408
	ds_read_b128 v[168:171], v231 offset:18432
	ds_read_b128 v[172:175], v231 offset:19456
	ds_read_b128 v[176:179], v231 offset:20480
	ds_read_b128 v[180:183], v231 offset:21504
	ds_read_b128 v[184:187], v231 offset:22528
	ds_read_b128 v[188:191], v231 offset:23552
	global_load_lds_dwordx4 v[192:193], off
	s_add_i32 m0, s35, 0x2000
	s_add_u32 s58, s42, 0x40000
	v_lshl_add_u64 v[194:195], s[42:43], 0, v[206:207]
	s_addc_u32 s59, s43, 0
	s_add_i32 s35, s56, s46
	global_load_lds_dwordx4 v[194:195], off
	v_lshl_add_u64 v[196:197], s[58:59], 0, v[202:203]
	s_mov_b32 m0, s35
	v_lshl_add_u64 v[198:199], s[44:45], 0, v[204:205]
	global_load_lds_dwordx4 v[196:197], off
	v_lshl_add_u64 v[196:197], s[58:59], 0, v[206:207]
	s_add_i32 m0, s35, 0x2000
	s_nop 0
	global_load_lds_dwordx4 v[196:197], off
	v_lshl_add_u64 v[196:197], s[44:45], 0, v[200:201]
	s_waitcnt vmcnt(8)
	s_waitcnt lgkmcnt(0)
	s_barrier
	s_setprio 0
	s_waitcnt lgkmcnt(0)
	v_mfma_f32_16x16x32_bf16 v[60:63], v[64:67], v[160:163], v[60:63]
	v_mfma_f32_16x16x32_bf16 v[56:59], v[72:75], v[160:163], v[56:59]
	v_mfma_f32_16x16x32_bf16 v[44:47], v[64:67], v[168:171], v[44:47]
	v_mfma_f32_16x16x32_bf16 v[40:43], v[72:75], v[168:171], v[40:43]
	v_mfma_f32_16x16x32_bf16 v[28:31], v[64:67], v[176:179], v[28:31]
	v_mfma_f32_16x16x32_bf16 v[24:27], v[72:75], v[176:179], v[24:27]
	v_mfma_f32_16x16x32_bf16 v[12:15], v[64:67], v[184:187], v[12:15]
	v_mfma_f32_16x16x32_bf16 v[8:11], v[72:75], v[184:187], v[8:11]
	v_mfma_f32_16x16x32_bf16 v[60:63], v[68:71], v[164:167], v[60:63]
	v_mfma_f32_16x16x32_bf16 v[56:59], v[76:79], v[164:167], v[56:59]
	v_mfma_f32_16x16x32_bf16 v[44:47], v[68:71], v[172:175], v[44:47]
	v_mfma_f32_16x16x32_bf16 v[40:43], v[76:79], v[172:175], v[40:43]
	v_mfma_f32_16x16x32_bf16 v[28:31], v[68:71], v[180:183], v[28:31]
	v_mfma_f32_16x16x32_bf16 v[24:27], v[76:79], v[180:183], v[24:27]
	v_mfma_f32_16x16x32_bf16 v[12:15], v[68:71], v[188:191], v[12:15]
	v_mfma_f32_16x16x32_bf16 v[8:11], v[76:79], v[188:191], v[8:11]
	s_setprio 1
	s_setprio 0
	v_mfma_f32_16x16x32_bf16 v[52:55], v[136:139], v[160:163], v[52:55]
	v_mfma_f32_16x16x32_bf16 v[48:51], v[144:147], v[160:163], v[48:51]
	v_mfma_f32_16x16x32_bf16 v[36:39], v[136:139], v[168:171], v[36:39]
	v_mfma_f32_16x16x32_bf16 v[32:35], v[144:147], v[168:171], v[32:35]
	v_mfma_f32_16x16x32_bf16 v[20:23], v[136:139], v[176:179], v[20:23]
	v_mfma_f32_16x16x32_bf16 v[16:19], v[144:147], v[176:179], v[16:19]
	v_mfma_f32_16x16x32_bf16 v[4:7], v[136:139], v[184:187], v[4:7]
	v_mfma_f32_16x16x32_bf16 v[0:3], v[144:147], v[184:187], v[0:3]
	v_mfma_f32_16x16x32_bf16 v[52:55], v[140:143], v[164:167], v[52:55]
	v_mfma_f32_16x16x32_bf16 v[48:51], v[148:151], v[164:167], v[48:51]
	v_mfma_f32_16x16x32_bf16 v[36:39], v[140:143], v[172:175], v[36:39]
	v_mfma_f32_16x16x32_bf16 v[32:35], v[148:151], v[172:175], v[32:35]
	v_mfma_f32_16x16x32_bf16 v[20:23], v[140:143], v[180:183], v[20:23]
	v_mfma_f32_16x16x32_bf16 v[16:19], v[148:151], v[180:183], v[16:19]
	v_mfma_f32_16x16x32_bf16 v[4:7], v[140:143], v[188:191], v[4:7]
	v_mfma_f32_16x16x32_bf16 v[0:3], v[148:151], v[188:191], v[0:3]
	s_setprio 1
	s_barrier
	s_add_i32 s35, 0, 0x18000
	s_add_i32 s57, 0, 0x1c000
	v_add_u32_e32 v76, s35, v227
	v_add_u32_e32 v148, s57, v227
	ds_read_b128 v[64:67], v76
	ds_read_b128 v[68:71], v76 offset:1024
	ds_read_b128 v[72:75], v76 offset:2048
	ds_read_b128 v[76:79], v76 offset:3072
	ds_read_b128 v[136:139], v148
	ds_read_b128 v[140:143], v148 offset:1024
	ds_read_b128 v[144:147], v148 offset:2048
	ds_read_b128 v[148:151], v148 offset:3072
	s_add_u32 s44, s44, 0x40000
	s_addc_u32 s45, s45, 0
	s_mov_b32 m0, s49
	v_lshl_add_u64 v[216:217], s[44:45], 0, v[200:201]
	ds_read_b128 v[160:163], v231 offset:32768
	ds_read_b128 v[164:167], v231 offset:33792
	ds_read_b128 v[168:171], v231 offset:34816
	ds_read_b128 v[172:175], v231 offset:35840
	ds_read_b128 v[176:179], v231 offset:36864
	ds_read_b128 v[180:183], v231 offset:37888
	ds_read_b128 v[184:187], v231 offset:38912
	ds_read_b128 v[188:191], v231 offset:39936
	global_load_lds_dwordx4 v[216:217], off
	v_lshl_add_u64 v[216:217], s[44:45], 0, v[204:205]
	s_mov_b32 m0, s50
	s_nop 0
	global_load_lds_dwordx4 v[216:217], off
	s_waitcnt vmcnt(8)
	s_waitcnt lgkmcnt(0)
	s_barrier
	s_setprio 0
	s_waitcnt lgkmcnt(0)
	v_mfma_f32_16x16x32_bf16 v[156:159], v[64:67], v[160:163], v[156:159]
	v_mfma_f32_16x16x32_bf16 v[152:155], v[72:75], v[160:163], v[152:155]
	v_mfma_f32_16x16x32_bf16 v[124:127], v[64:67], v[168:171], v[124:127]
	v_mfma_f32_16x16x32_bf16 v[120:123], v[72:75], v[168:171], v[120:123]
	v_mfma_f32_16x16x32_bf16 v[108:111], v[64:67], v[176:179], v[108:111]
	v_mfma_f32_16x16x32_bf16 v[104:107], v[72:75], v[176:179], v[104:107]
	v_mfma_f32_16x16x32_bf16 v[92:95], v[64:67], v[184:187], v[92:95]
	v_mfma_f32_16x16x32_bf16 v[88:91], v[72:75], v[184:187], v[88:91]
	v_mfma_f32_16x16x32_bf16 v[156:159], v[68:71], v[164:167], v[156:159]
	v_mfma_f32_16x16x32_bf16 v[152:155], v[76:79], v[164:167], v[152:155]
	v_mfma_f32_16x16x32_bf16 v[124:127], v[68:71], v[172:175], v[124:127]
	v_mfma_f32_16x16x32_bf16 v[120:123], v[76:79], v[172:175], v[120:123]
	v_mfma_f32_16x16x32_bf16 v[108:111], v[68:71], v[180:183], v[108:111]
	v_mfma_f32_16x16x32_bf16 v[104:107], v[76:79], v[180:183], v[104:107]
	v_mfma_f32_16x16x32_bf16 v[92:95], v[68:71], v[188:191], v[92:95]
	v_mfma_f32_16x16x32_bf16 v[88:91], v[76:79], v[188:191], v[88:91]
	s_setprio 1
	s_setprio 0
	v_mfma_f32_16x16x32_bf16 v[132:135], v[136:139], v[160:163], v[132:135]
	v_mfma_f32_16x16x32_bf16 v[128:131], v[144:147], v[160:163], v[128:131]
	v_mfma_f32_16x16x32_bf16 v[116:119], v[136:139], v[168:171], v[116:119]
	v_mfma_f32_16x16x32_bf16 v[112:115], v[144:147], v[168:171], v[112:115]
	v_mfma_f32_16x16x32_bf16 v[100:103], v[136:139], v[176:179], v[100:103]
	v_mfma_f32_16x16x32_bf16 v[96:99], v[144:147], v[176:179], v[96:99]
	v_mfma_f32_16x16x32_bf16 v[84:87], v[136:139], v[184:187], v[84:87]
	v_mfma_f32_16x16x32_bf16 v[80:83], v[144:147], v[184:187], v[80:83]
	v_mfma_f32_16x16x32_bf16 v[132:135], v[140:143], v[164:167], v[132:135]
	v_mfma_f32_16x16x32_bf16 v[128:131], v[148:151], v[164:167], v[128:131]
	v_mfma_f32_16x16x32_bf16 v[116:119], v[140:143], v[172:175], v[116:119]
	v_mfma_f32_16x16x32_bf16 v[112:115], v[148:151], v[172:175], v[112:115]
	v_mfma_f32_16x16x32_bf16 v[100:103], v[140:143], v[180:183], v[100:103]
	v_mfma_f32_16x16x32_bf16 v[96:99], v[148:151], v[180:183], v[96:99]
	v_mfma_f32_16x16x32_bf16 v[84:87], v[140:143], v[188:191], v[84:87]
	v_mfma_f32_16x16x32_bf16 v[80:83], v[148:151], v[188:191], v[80:83]
	s_setprio 1
	s_barrier
	v_lshl_add_u64 v[252:253], v[196:197], 0, s[16:17]
	s_mov_b32 m0, s53
	s_nop 0
	global_load_lds_dwordx4 v[252:253], off
	v_lshl_add_u64 v[252:253], v[198:199], 0, s[16:17]
	s_mov_b32 m0, s54
	s_nop 0
	global_load_lds_dwordx4 v[252:253], off
	s_add_i32 s35, s35, s46
	v_lshl_add_u64 v[192:193], v[192:193], 0, s[16:17]
	s_mov_b32 m0, s35
	ds_read_b128 v[160:163], v231 offset:49152
	ds_read_b128 v[164:167], v231 offset:50176
	ds_read_b128 v[168:171], v231 offset:51200
	ds_read_b128 v[172:175], v231 offset:52224
	ds_read_b128 v[176:179], v231 offset:53248
	ds_read_b128 v[180:183], v231 offset:54272
	ds_read_b128 v[184:187], v231 offset:55296
	ds_read_b128 v[188:191], v231 offset:56320
	global_load_lds_dwordx4 v[192:193], off
	s_add_i32 m0, s35, 0x2000
	s_add_u32 s42, s42, 0x40080
	v_lshl_add_u64 v[192:193], v[194:195], 0, s[16:17]
	s_addc_u32 s43, s43, 0
	s_add_i32 s35, s57, s46
	global_load_lds_dwordx4 v[192:193], off
	v_lshl_add_u64 v[192:193], s[42:43], 0, v[202:203]
	s_mov_b32 m0, s35
	s_nop 0
	global_load_lds_dwordx4 v[192:193], off
	v_lshl_add_u64 v[192:193], s[42:43], 0, v[206:207]
	s_add_i32 m0, s35, 0x2000
	s_nop 0
	global_load_lds_dwordx4 v[192:193], off
	v_lshl_add_u64 v[192:193], v[196:197], 0, s[16:17]
	v_lshl_add_u64 v[192:193], v[198:199], 0, s[16:17]
	s_waitcnt vmcnt(8)
	s_waitcnt lgkmcnt(0)
	s_barrier
	s_setprio 0
	s_waitcnt lgkmcnt(0)
	v_mfma_f32_16x16x32_bf16 v[60:63], v[64:67], v[160:163], v[60:63]
	v_mfma_f32_16x16x32_bf16 v[56:59], v[72:75], v[160:163], v[56:59]
	v_mfma_f32_16x16x32_bf16 v[44:47], v[64:67], v[168:171], v[44:47]
	v_mfma_f32_16x16x32_bf16 v[40:43], v[72:75], v[168:171], v[40:43]
	v_mfma_f32_16x16x32_bf16 v[28:31], v[64:67], v[176:179], v[28:31]
	v_mfma_f32_16x16x32_bf16 v[24:27], v[72:75], v[176:179], v[24:27]
	v_mfma_f32_16x16x32_bf16 v[12:15], v[64:67], v[184:187], v[12:15]
	v_mfma_f32_16x16x32_bf16 v[8:11], v[72:75], v[184:187], v[8:11]
	v_mfma_f32_16x16x32_bf16 v[60:63], v[68:71], v[164:167], v[60:63]
	v_mfma_f32_16x16x32_bf16 v[56:59], v[76:79], v[164:167], v[56:59]
	v_mfma_f32_16x16x32_bf16 v[44:47], v[68:71], v[172:175], v[44:47]
	v_mfma_f32_16x16x32_bf16 v[40:43], v[76:79], v[172:175], v[40:43]
	v_mfma_f32_16x16x32_bf16 v[28:31], v[68:71], v[180:183], v[28:31]
	v_mfma_f32_16x16x32_bf16 v[24:27], v[76:79], v[180:183], v[24:27]
	v_mfma_f32_16x16x32_bf16 v[12:15], v[68:71], v[188:191], v[12:15]
	v_mfma_f32_16x16x32_bf16 v[8:11], v[76:79], v[188:191], v[8:11]
	s_setprio 1
	s_setprio 0
	v_mfma_f32_16x16x32_bf16 v[52:55], v[136:139], v[160:163], v[52:55]
	v_mfma_f32_16x16x32_bf16 v[48:51], v[144:147], v[160:163], v[48:51]
	v_mfma_f32_16x16x32_bf16 v[36:39], v[136:139], v[168:171], v[36:39]
	v_mfma_f32_16x16x32_bf16 v[32:35], v[144:147], v[168:171], v[32:35]
	v_mfma_f32_16x16x32_bf16 v[20:23], v[136:139], v[176:179], v[20:23]
	v_mfma_f32_16x16x32_bf16 v[16:19], v[144:147], v[176:179], v[16:19]
	v_mfma_f32_16x16x32_bf16 v[4:7], v[136:139], v[184:187], v[4:7]
	v_mfma_f32_16x16x32_bf16 v[0:3], v[144:147], v[184:187], v[0:3]
	v_mfma_f32_16x16x32_bf16 v[52:55], v[140:143], v[164:167], v[52:55]
	v_mfma_f32_16x16x32_bf16 v[48:51], v[148:151], v[164:167], v[48:51]
	v_mfma_f32_16x16x32_bf16 v[36:39], v[140:143], v[172:175], v[36:39]
	v_mfma_f32_16x16x32_bf16 v[32:35], v[148:151], v[172:175], v[32:35]
	v_mfma_f32_16x16x32_bf16 v[20:23], v[140:143], v[180:183], v[20:23]
	v_mfma_f32_16x16x32_bf16 v[16:19], v[148:151], v[180:183], v[16:19]
	v_mfma_f32_16x16x32_bf16 v[4:7], v[140:143], v[188:191], v[4:7]
	v_mfma_f32_16x16x32_bf16 v[0:3], v[148:151], v[188:191], v[0:3]
	s_setprio 1
	s_barrier
	s_add_i32 s34, s34, 2
	s_add_u32 s40, s40, 0x100
	s_addc_u32 s41, s41, 0
	s_add_u32 s30, s30, 0x100
	s_addc_u32 s33, s33, 0
	s_cmp_gt_u32 s34, 13
	s_cbranch_scc0 .LBB5_463
	s_nop 0
	s_nop 0
	s_nop 0
	s_nop 0
	s_nop 0
	s_nop 0
	s_nop 0
	s_nop 0
	s_setprio 0
	s_nop 0
	s_nop 0
	s_nop 0
	s_nop 0
	s_nop 0
	s_nop 0
	s_nop 0
	s_nop 0
	s_nop 0
	s_nop 0
	s_nop 0
	s_nop 0
	s_nop 0
	s_and_b64 vcc, exec, s[14:15]
	s_cbranch_vccz .LBB5_466
	s_barrier

.Lskw_P4:
	s_waitcnt lgkmcnt(0)
	s_barrier
	s_setprio 0
	s_waitcnt lgkmcnt(0)
	v_mfma_f32_16x16x32_bf16 v[124:127], v[128:131], v[160:163], v[124:127]
	v_mfma_f32_16x16x32_bf16 v[120:123], v[136:139], v[160:163], v[120:123]
	v_mfma_f32_16x16x32_bf16 v[108:111], v[128:131], v[168:171], v[108:111]
	v_mfma_f32_16x16x32_bf16 v[104:107], v[136:139], v[168:171], v[104:107]
	v_mfma_f32_16x16x32_bf16 v[92:95], v[128:131], v[192:195], v[92:95]
	v_mfma_f32_16x16x32_bf16 v[88:91], v[136:139], v[192:195], v[88:91]
	v_mfma_f32_16x16x32_bf16 v[76:79], v[128:131], v[200:203], v[76:79]
	v_mfma_f32_16x16x32_bf16 v[72:75], v[136:139], v[200:203], v[72:75]
	v_mfma_f32_16x16x32_bf16 v[124:127], v[132:135], v[164:167], v[124:127]
	v_mfma_f32_16x16x32_bf16 v[120:123], v[140:143], v[164:167], v[120:123]
	v_mfma_f32_16x16x32_bf16 v[108:111], v[132:135], v[172:175], v[108:111]
	v_mfma_f32_16x16x32_bf16 v[104:107], v[140:143], v[172:175], v[104:107]
	v_mfma_f32_16x16x32_bf16 v[92:95], v[132:135], v[196:199], v[92:95]
	v_mfma_f32_16x16x32_bf16 v[88:91], v[140:143], v[196:199], v[88:91]
	v_mfma_f32_16x16x32_bf16 v[76:79], v[132:135], v[212:215], v[76:79]
	v_mfma_f32_16x16x32_bf16 v[72:75], v[140:143], v[212:215], v[72:75]
	s_setprio 1
	s_setprio 0
	v_mfma_f32_16x16x32_bf16 v[116:119], v[144:147], v[160:163], v[116:119]
	v_mfma_f32_16x16x32_bf16 v[112:115], v[152:155], v[160:163], v[112:115]
	v_mfma_f32_16x16x32_bf16 v[100:103], v[144:147], v[168:171], v[100:103]
	v_mfma_f32_16x16x32_bf16 v[96:99], v[152:155], v[168:171], v[96:99]
	v_mfma_f32_16x16x32_bf16 v[84:87], v[144:147], v[192:195], v[84:87]
	v_mfma_f32_16x16x32_bf16 v[80:83], v[152:155], v[192:195], v[80:83]
	v_mfma_f32_16x16x32_bf16 v[68:71], v[144:147], v[200:203], v[68:71]
	v_mfma_f32_16x16x32_bf16 v[64:67], v[152:155], v[200:203], v[64:67]
	v_mfma_f32_16x16x32_bf16 v[116:119], v[148:151], v[164:167], v[116:119]
	v_mfma_f32_16x16x32_bf16 v[112:115], v[156:159], v[164:167], v[112:115]
	v_mfma_f32_16x16x32_bf16 v[100:103], v[148:151], v[172:175], v[100:103]
	v_mfma_f32_16x16x32_bf16 v[96:99], v[156:159], v[172:175], v[96:99]
	v_mfma_f32_16x16x32_bf16 v[84:87], v[148:151], v[196:199], v[84:87]
	v_mfma_f32_16x16x32_bf16 v[80:83], v[156:159], v[196:199], v[80:83]
	v_mfma_f32_16x16x32_bf16 v[68:71], v[148:151], v[212:215], v[68:71]
	v_mfma_f32_16x16x32_bf16 v[64:67], v[156:159], v[212:215], v[64:67]
	s_setprio 1
	s_barrier
	v_lshl_add_u64 v[252:253], s[44:45], 0, v[176:177]
	s_mov_b32 m0, s31
	s_nop 0
	global_load_lds_dwordx4 v[252:253], off
	v_lshl_add_u64 v[252:253], s[44:45], 0, v[180:181]
	s_mov_b32 m0, s33
	s_nop 0
	global_load_lds_dwordx4 v[252:253], off
	s_add_i32 s58, s51, s30
	v_lshl_add_u64 v[216:217], s[42:43], 0, v[178:179]
	s_mov_b32 m0, s58
	ds_read_b128 v[160:163], v211 offset:16384
	ds_read_b128 v[164:167], v211 offset:17408
	ds_read_b128 v[168:171], v211 offset:18432
	ds_read_b128 v[172:175], v211 offset:19456
	ds_read_b128 v[192:195], v211 offset:20480
	ds_read_b128 v[196:199], v211 offset:21504
	ds_read_b128 v[200:203], v211 offset:22528
	ds_read_b128 v[212:215], v211 offset:23552
	global_load_lds_dwordx4 v[216:217], off
	s_add_i32 m0, s58, 0x2000
	s_add_u32 s58, s42, 0x40000
	v_lshl_add_u64 v[218:219], s[42:43], 0, v[182:183]
	s_addc_u32 s59, s43, 0
	s_add_i32 s60, s52, s30
	global_load_lds_dwordx4 v[218:219], off
	v_lshl_add_u64 v[220:221], s[58:59], 0, v[178:179]
	s_mov_b32 m0, s60
	v_lshl_add_u64 v[222:223], s[44:45], 0, v[180:181]
	global_load_lds_dwordx4 v[220:221], off
	v_lshl_add_u64 v[220:221], s[58:59], 0, v[182:183]
	s_add_i32 m0, s60, 0x2000
	s_nop 0
	global_load_lds_dwordx4 v[220:221], off
	v_lshl_add_u64 v[220:221], s[44:45], 0, v[176:177]
	s_waitcnt vmcnt(8)
	s_waitcnt lgkmcnt(0)
	s_barrier
	s_setprio 0
	s_waitcnt lgkmcnt(0)
	v_mfma_f32_16x16x32_bf16 v[60:63], v[128:131], v[160:163], v[60:63]
	v_mfma_f32_16x16x32_bf16 v[56:59], v[136:139], v[160:163], v[56:59]
	v_mfma_f32_16x16x32_bf16 v[44:47], v[128:131], v[168:171], v[44:47]
	v_mfma_f32_16x16x32_bf16 v[40:43], v[136:139], v[168:171], v[40:43]
	v_mfma_f32_16x16x32_bf16 v[28:31], v[128:131], v[192:195], v[28:31]
	v_mfma_f32_16x16x32_bf16 v[24:27], v[136:139], v[192:195], v[24:27]
	v_mfma_f32_16x16x32_bf16 v[12:15], v[128:131], v[200:203], v[12:15]
	v_mfma_f32_16x16x32_bf16 v[8:11], v[136:139], v[200:203], v[8:11]
	v_mfma_f32_16x16x32_bf16 v[60:63], v[132:135], v[164:167], v[60:63]
	v_mfma_f32_16x16x32_bf16 v[56:59], v[140:143], v[164:167], v[56:59]
	v_mfma_f32_16x16x32_bf16 v[44:47], v[132:135], v[172:175], v[44:47]
	v_mfma_f32_16x16x32_bf16 v[40:43], v[140:143], v[172:175], v[40:43]
	v_mfma_f32_16x16x32_bf16 v[28:31], v[132:135], v[196:199], v[28:31]
	v_mfma_f32_16x16x32_bf16 v[24:27], v[140:143], v[196:199], v[24:27]
	v_mfma_f32_16x16x32_bf16 v[12:15], v[132:135], v[212:215], v[12:15]
	v_mfma_f32_16x16x32_bf16 v[8:11], v[140:143], v[212:215], v[8:11]
	s_setprio 1
	s_setprio 0
	v_mfma_f32_16x16x32_bf16 v[52:55], v[144:147], v[160:163], v[52:55]
	v_mfma_f32_16x16x32_bf16 v[48:51], v[152:155], v[160:163], v[48:51]
	v_mfma_f32_16x16x32_bf16 v[36:39], v[144:147], v[168:171], v[36:39]
	v_mfma_f32_16x16x32_bf16 v[32:35], v[152:155], v[168:171], v[32:35]
	v_mfma_f32_16x16x32_bf16 v[20:23], v[144:147], v[192:195], v[20:23]
	v_mfma_f32_16x16x32_bf16 v[16:19], v[152:155], v[192:195], v[16:19]
	v_mfma_f32_16x16x32_bf16 v[4:7], v[144:147], v[200:203], v[4:7]
	v_mfma_f32_16x16x32_bf16 v[0:3], v[152:155], v[200:203], v[0:3]
	v_mfma_f32_16x16x32_bf16 v[52:55], v[148:151], v[164:167], v[52:55]
	v_mfma_f32_16x16x32_bf16 v[48:51], v[156:159], v[164:167], v[48:51]
	v_mfma_f32_16x16x32_bf16 v[36:39], v[148:151], v[172:175], v[36:39]
	v_mfma_f32_16x16x32_bf16 v[32:35], v[156:159], v[172:175], v[32:35]
	v_mfma_f32_16x16x32_bf16 v[20:23], v[148:151], v[196:199], v[20:23]
	v_mfma_f32_16x16x32_bf16 v[16:19], v[156:159], v[196:199], v[16:19]
	v_mfma_f32_16x16x32_bf16 v[4:7], v[148:151], v[212:215], v[4:7]
	v_mfma_f32_16x16x32_bf16 v[0:3], v[156:159], v[212:215], v[0:3]
	s_setprio 1
	s_barrier
	s_add_i32 s58, 0, 0x18000
	s_add_i32 s59, 0, 0x1c000
	v_add_u32_e32 v140, s58, v205
	v_add_u32_e32 v156, s59, v205
	ds_read_b128 v[128:131], v140
	ds_read_b128 v[132:135], v140 offset:1024
	ds_read_b128 v[136:139], v140 offset:2048
	ds_read_b128 v[140:143], v140 offset:3072
	ds_read_b128 v[144:147], v156
	ds_read_b128 v[148:151], v156 offset:1024
	ds_read_b128 v[152:155], v156 offset:2048
	ds_read_b128 v[156:159], v156 offset:3072
	s_add_u32 s44, s44, 0x40000
	s_addc_u32 s45, s45, 0
	s_mov_b32 m0, s34
	v_lshl_add_u64 v[224:225], s[44:45], 0, v[176:177]
	ds_read_b128 v[160:163], v211 offset:32768
	ds_read_b128 v[164:167], v211 offset:33792
	ds_read_b128 v[168:171], v211 offset:34816
	ds_read_b128 v[172:175], v211 offset:35840
	ds_read_b128 v[192:195], v211 offset:36864
	ds_read_b128 v[196:199], v211 offset:37888
	ds_read_b128 v[200:203], v211 offset:38912
	ds_read_b128 v[212:215], v211 offset:39936
	global_load_lds_dwordx4 v[224:225], off
	v_lshl_add_u64 v[224:225], s[44:45], 0, v[180:181]
	s_mov_b32 m0, s35
	s_nop 0
	global_load_lds_dwordx4 v[224:225], off
	s_waitcnt vmcnt(8)
	s_waitcnt lgkmcnt(0)
	s_barrier
	s_setprio 0
	s_waitcnt lgkmcnt(0)
	v_mfma_f32_16x16x32_bf16 v[124:127], v[128:131], v[160:163], v[124:127]
	v_mfma_f32_16x16x32_bf16 v[120:123], v[136:139], v[160:163], v[120:123]
	v_mfma_f32_16x16x32_bf16 v[108:111], v[128:131], v[168:171], v[108:111]
	v_mfma_f32_16x16x32_bf16 v[104:107], v[136:139], v[168:171], v[104:107]
	v_mfma_f32_16x16x32_bf16 v[92:95], v[128:131], v[192:195], v[92:95]
	v_mfma_f32_16x16x32_bf16 v[88:91], v[136:139], v[192:195], v[88:91]
	v_mfma_f32_16x16x32_bf16 v[76:79], v[128:131], v[200:203], v[76:79]
	v_mfma_f32_16x16x32_bf16 v[72:75], v[136:139], v[200:203], v[72:75]
	v_mfma_f32_16x16x32_bf16 v[124:127], v[132:135], v[164:167], v[124:127]
	v_mfma_f32_16x16x32_bf16 v[120:123], v[140:143], v[164:167], v[120:123]
	v_mfma_f32_16x16x32_bf16 v[108:111], v[132:135], v[172:175], v[108:111]
	v_mfma_f32_16x16x32_bf16 v[104:107], v[140:143], v[172:175], v[104:107]
	v_mfma_f32_16x16x32_bf16 v[92:95], v[132:135], v[196:199], v[92:95]
	v_mfma_f32_16x16x32_bf16 v[88:91], v[140:143], v[196:199], v[88:91]
	v_mfma_f32_16x16x32_bf16 v[76:79], v[132:135], v[212:215], v[76:79]
	v_mfma_f32_16x16x32_bf16 v[72:75], v[140:143], v[212:215], v[72:75]
	s_setprio 1
	s_setprio 0
	v_mfma_f32_16x16x32_bf16 v[116:119], v[144:147], v[160:163], v[116:119]
	v_mfma_f32_16x16x32_bf16 v[112:115], v[152:155], v[160:163], v[112:115]
	v_mfma_f32_16x16x32_bf16 v[100:103], v[144:147], v[168:171], v[100:103]
	v_mfma_f32_16x16x32_bf16 v[96:99], v[152:155], v[168:171], v[96:99]
	v_mfma_f32_16x16x32_bf16 v[84:87], v[144:147], v[192:195], v[84:87]
	v_mfma_f32_16x16x32_bf16 v[80:83], v[152:155], v[192:195], v[80:83]
	v_mfma_f32_16x16x32_bf16 v[68:71], v[144:147], v[200:203], v[68:71]
	v_mfma_f32_16x16x32_bf16 v[64:67], v[152:155], v[200:203], v[64:67]
	v_mfma_f32_16x16x32_bf16 v[116:119], v[148:151], v[164:167], v[116:119]
	v_mfma_f32_16x16x32_bf16 v[112:115], v[156:159], v[164:167], v[112:115]
	v_mfma_f32_16x16x32_bf16 v[100:103], v[148:151], v[172:175], v[100:103]
	v_mfma_f32_16x16x32_bf16 v[96:99], v[156:159], v[172:175], v[96:99]
	v_mfma_f32_16x16x32_bf16 v[84:87], v[148:151], v[196:199], v[84:87]
	v_mfma_f32_16x16x32_bf16 v[80:83], v[156:159], v[196:199], v[80:83]
	v_mfma_f32_16x16x32_bf16 v[68:71], v[148:151], v[212:215], v[68:71]
	v_mfma_f32_16x16x32_bf16 v[64:67], v[156:159], v[212:215], v[64:67]
	s_setprio 1
	s_barrier
	v_lshl_add_u64 v[252:253], v[220:221], 0, s[16:17]
	s_mov_b32 m0, s49
	s_nop 0
	global_load_lds_dwordx4 v[252:253], off
	v_lshl_add_u64 v[252:253], v[222:223], 0, s[16:17]
	s_mov_b32 m0, s50
	s_nop 0
	global_load_lds_dwordx4 v[252:253], off
	s_add_i32 s44, s58, s30
	v_lshl_add_u64 v[216:217], v[216:217], 0, s[16:17]
	s_mov_b32 m0, s44
	ds_read_b128 v[160:163], v211 offset:49152
	ds_read_b128 v[164:167], v211 offset:50176
	ds_read_b128 v[168:171], v211 offset:51200
	ds_read_b128 v[172:175], v211 offset:52224
	ds_read_b128 v[192:195], v211 offset:53248
	ds_read_b128 v[196:199], v211 offset:54272
	ds_read_b128 v[200:203], v211 offset:55296
	ds_read_b128 v[212:215], v211 offset:56320
	global_load_lds_dwordx4 v[216:217], off
	s_add_i32 m0, s44, 0x2000
	s_add_u32 s42, s42, 0x40080
	v_lshl_add_u64 v[216:217], v[218:219], 0, s[16:17]
	s_addc_u32 s43, s43, 0
	s_add_i32 s44, s59, s30
	global_load_lds_dwordx4 v[216:217], off
	v_lshl_add_u64 v[216:217], s[42:43], 0, v[178:179]
	s_mov_b32 m0, s44
	s_nop 0
	global_load_lds_dwordx4 v[216:217], off
	v_lshl_add_u64 v[216:217], s[42:43], 0, v[182:183]
	s_add_i32 m0, s44, 0x2000
	s_nop 0
	global_load_lds_dwordx4 v[216:217], off
	v_lshl_add_u64 v[216:217], v[220:221], 0, s[16:17]
	v_lshl_add_u64 v[216:217], v[222:223], 0, s[16:17]
	s_waitcnt vmcnt(8)
	s_waitcnt lgkmcnt(0)
	s_barrier
	s_setprio 0
	s_waitcnt lgkmcnt(0)
	v_mfma_f32_16x16x32_bf16 v[60:63], v[128:131], v[160:163], v[60:63]
	v_mfma_f32_16x16x32_bf16 v[56:59], v[136:139], v[160:163], v[56:59]
	v_mfma_f32_16x16x32_bf16 v[44:47], v[128:131], v[168:171], v[44:47]
	v_mfma_f32_16x16x32_bf16 v[40:43], v[136:139], v[168:171], v[40:43]
	v_mfma_f32_16x16x32_bf16 v[28:31], v[128:131], v[192:195], v[28:31]
	v_mfma_f32_16x16x32_bf16 v[24:27], v[136:139], v[192:195], v[24:27]
	v_mfma_f32_16x16x32_bf16 v[12:15], v[128:131], v[200:203], v[12:15]
	v_mfma_f32_16x16x32_bf16 v[8:11], v[136:139], v[200:203], v[8:11]
	v_mfma_f32_16x16x32_bf16 v[60:63], v[132:135], v[164:167], v[60:63]
	v_mfma_f32_16x16x32_bf16 v[56:59], v[140:143], v[164:167], v[56:59]
	v_mfma_f32_16x16x32_bf16 v[44:47], v[132:135], v[172:175], v[44:47]
	v_mfma_f32_16x16x32_bf16 v[40:43], v[140:143], v[172:175], v[40:43]
	v_mfma_f32_16x16x32_bf16 v[28:31], v[132:135], v[196:199], v[28:31]
	v_mfma_f32_16x16x32_bf16 v[24:27], v[140:143], v[196:199], v[24:27]
	v_mfma_f32_16x16x32_bf16 v[12:15], v[132:135], v[212:215], v[12:15]
	v_mfma_f32_16x16x32_bf16 v[8:11], v[140:143], v[212:215], v[8:11]
	s_setprio 1
	s_setprio 0
	v_mfma_f32_16x16x32_bf16 v[52:55], v[144:147], v[160:163], v[52:55]
	v_mfma_f32_16x16x32_bf16 v[48:51], v[152:155], v[160:163], v[48:51]
	v_mfma_f32_16x16x32_bf16 v[36:39], v[144:147], v[168:171], v[36:39]
	v_mfma_f32_16x16x32_bf16 v[32:35], v[152:155], v[168:171], v[32:35]
	v_mfma_f32_16x16x32_bf16 v[20:23], v[144:147], v[192:195], v[20:23]
	v_mfma_f32_16x16x32_bf16 v[16:19], v[152:155], v[192:195], v[16:19]
	v_mfma_f32_16x16x32_bf16 v[4:7], v[144:147], v[200:203], v[4:7]
	v_mfma_f32_16x16x32_bf16 v[0:3], v[152:155], v[200:203], v[0:3]
	v_mfma_f32_16x16x32_bf16 v[52:55], v[148:151], v[164:167], v[52:55]
	v_mfma_f32_16x16x32_bf16 v[48:51], v[156:159], v[164:167], v[48:51]
	v_mfma_f32_16x16x32_bf16 v[36:39], v[148:151], v[172:175], v[36:39]
	v_mfma_f32_16x16x32_bf16 v[32:35], v[156:159], v[172:175], v[32:35]
	v_mfma_f32_16x16x32_bf16 v[20:23], v[148:151], v[196:199], v[20:23]
	v_mfma_f32_16x16x32_bf16 v[16:19], v[156:159], v[196:199], v[16:19]
	v_mfma_f32_16x16x32_bf16 v[4:7], v[148:151], v[212:215], v[4:7]
	v_mfma_f32_16x16x32_bf16 v[0:3], v[156:159], v[212:215], v[0:3]
	s_setprio 1
	s_barrier
	s_add_i32 s57, s57, 2
	s_add_u32 s40, s40, 0x100
	s_addc_u32 s41, s41, 0
	s_add_u32 s55, s55, 0x100
	s_addc_u32 s56, s56, 0
	s_cmp_gt_u32 s57, 13
	s_cbranch_scc0 .LBB5_536
	s_nop 0
	s_nop 0
	s_nop 0
	s_nop 0
	s_nop 0
	s_nop 0
	s_nop 0
	s_nop 0
	s_setprio 0
	s_nop 0
	s_nop 0
	s_nop 0
	s_nop 0
	s_nop 0
	s_nop 0
	s_nop 0
	s_nop 0
	s_nop 0
	s_nop 0
	s_nop 0
	s_nop 0
	s_nop 0
	s_and_b64 vcc, exec, s[14:15]
	s_cbranch_vccz .LBB5_539
	s_barrier

.Lskw_P5:
	s_waitcnt lgkmcnt(0)
	s_barrier
	s_setprio 0
	s_waitcnt lgkmcnt(0)
	v_mfma_f32_16x16x32_bf16 v[140:143], v[32:35], v[192:195], v[140:143]
	v_mfma_f32_16x16x32_bf16 v[136:139], v[40:43], v[192:195], v[136:139]
	v_mfma_f32_16x16x32_bf16 v[124:127], v[32:35], v[200:203], v[124:127]
	v_mfma_f32_16x16x32_bf16 v[120:123], v[40:43], v[200:203], v[120:123]
	v_mfma_f32_16x16x32_bf16 v[108:111], v[32:35], v[208:211], v[108:111]
	v_mfma_f32_16x16x32_bf16 v[104:107], v[40:43], v[208:211], v[104:107]
	v_mfma_f32_16x16x32_bf16 v[92:95], v[32:35], v[216:219], v[92:95]
	v_mfma_f32_16x16x32_bf16 v[88:91], v[40:43], v[216:219], v[88:91]
	v_mfma_f32_16x16x32_bf16 v[140:143], v[36:39], v[196:199], v[140:143]
	v_mfma_f32_16x16x32_bf16 v[136:139], v[44:47], v[196:199], v[136:139]
	v_mfma_f32_16x16x32_bf16 v[124:127], v[36:39], v[204:207], v[124:127]
	v_mfma_f32_16x16x32_bf16 v[120:123], v[44:47], v[204:207], v[120:123]
	v_mfma_f32_16x16x32_bf16 v[108:111], v[36:39], v[212:215], v[108:111]
	v_mfma_f32_16x16x32_bf16 v[104:107], v[44:47], v[212:215], v[104:107]
	v_mfma_f32_16x16x32_bf16 v[92:95], v[36:39], v[220:223], v[92:95]
	v_mfma_f32_16x16x32_bf16 v[88:91], v[44:47], v[220:223], v[88:91]
	s_setprio 1
	s_setprio 0
	v_mfma_f32_16x16x32_bf16 v[132:135], v[144:147], v[192:195], v[132:135]
	v_mfma_f32_16x16x32_bf16 v[128:131], v[152:155], v[192:195], v[128:131]
	v_mfma_f32_16x16x32_bf16 v[116:119], v[144:147], v[200:203], v[116:119]
	v_mfma_f32_16x16x32_bf16 v[112:115], v[152:155], v[200:203], v[112:115]
	v_mfma_f32_16x16x32_bf16 v[100:103], v[144:147], v[208:211], v[100:103]
	v_mfma_f32_16x16x32_bf16 v[96:99], v[152:155], v[208:211], v[96:99]
	v_mfma_f32_16x16x32_bf16 v[84:87], v[144:147], v[216:219], v[84:87]
	v_mfma_f32_16x16x32_bf16 v[80:83], v[152:155], v[216:219], v[80:83]
	v_mfma_f32_16x16x32_bf16 v[132:135], v[148:151], v[196:199], v[132:135]
	v_mfma_f32_16x16x32_bf16 v[128:131], v[156:159], v[196:199], v[128:131]
	v_mfma_f32_16x16x32_bf16 v[116:119], v[148:151], v[204:207], v[116:119]
	v_mfma_f32_16x16x32_bf16 v[112:115], v[156:159], v[204:207], v[112:115]
	v_mfma_f32_16x16x32_bf16 v[100:103], v[148:151], v[212:215], v[100:103]
	v_mfma_f32_16x16x32_bf16 v[96:99], v[156:159], v[212:215], v[96:99]
	v_mfma_f32_16x16x32_bf16 v[84:87], v[148:151], v[220:223], v[84:87]
	v_mfma_f32_16x16x32_bf16 v[80:83], v[156:159], v[220:223], v[80:83]
	s_setprio 1
	s_barrier
	v_lshl_add_u64 v[252:253], s[56:57], 0, v[160:161]
	s_mov_b32 m0, s61
	s_nop 0
	global_load_lds_dwordx4 v[252:253], off
	v_lshl_add_u64 v[252:253], s[56:57], 0, v[164:165]
	s_mov_b32 m0, s62
	s_nop 0
	global_load_lds_dwordx4 v[252:253], off
	s_add_i32 s34, s80, s60
	v_lshl_add_u64 v[180:181], s[8:9], 0, v[162:163]
	s_mov_b32 m0, s34
	ds_read_b128 v[192:195], v188 offset:16384
	ds_read_b128 v[196:199], v188 offset:17408
	ds_read_b128 v[200:203], v188 offset:18432
	ds_read_b128 v[204:207], v188 offset:19456
	ds_read_b128 v[208:211], v188 offset:20480
	ds_read_b128 v[212:215], v188 offset:21504
	ds_read_b128 v[216:219], v188 offset:22528
	ds_read_b128 v[220:223], v188 offset:23552
	global_load_lds_dwordx4 v[180:181], off
	s_add_i32 m0, s34, 0x2000
	s_add_u32 s34, s8, 0x40000
	v_lshl_add_u64 v[224:225], s[8:9], 0, v[166:167]
	s_addc_u32 s35, s9, 0
	s_add_i32 s49, s81, s60
	global_load_lds_dwordx4 v[224:225], off
	v_lshl_add_u64 v[226:227], s[34:35], 0, v[162:163]
	s_mov_b32 m0, s49
	v_lshl_add_u64 v[228:229], s[56:57], 0, v[164:165]
	global_load_lds_dwordx4 v[226:227], off
	v_lshl_add_u64 v[226:227], s[34:35], 0, v[166:167]
	s_add_i32 m0, s49, 0x2000
	s_nop 0
	global_load_lds_dwordx4 v[226:227], off
	v_lshl_add_u64 v[226:227], s[56:57], 0, v[160:161]
	s_waitcnt vmcnt(8)
	s_waitcnt lgkmcnt(0)
	s_barrier
	s_setprio 0
	s_waitcnt lgkmcnt(0)
	v_mfma_f32_16x16x32_bf16 v[76:79], v[32:35], v[192:195], v[76:79]
	v_mfma_f32_16x16x32_bf16 v[72:75], v[40:43], v[192:195], v[72:75]
	v_mfma_f32_16x16x32_bf16 v[60:63], v[32:35], v[200:203], v[60:63]
	v_mfma_f32_16x16x32_bf16 v[56:59], v[40:43], v[200:203], v[56:59]
	v_mfma_f32_16x16x32_bf16 v[28:31], v[32:35], v[208:211], v[28:31]
	v_mfma_f32_16x16x32_bf16 v[24:27], v[40:43], v[208:211], v[24:27]
	v_mfma_f32_16x16x32_bf16 v[12:15], v[32:35], v[216:219], v[12:15]
	v_mfma_f32_16x16x32_bf16 v[8:11], v[40:43], v[216:219], v[8:11]
	v_mfma_f32_16x16x32_bf16 v[76:79], v[36:39], v[196:199], v[76:79]
	v_mfma_f32_16x16x32_bf16 v[72:75], v[44:47], v[196:199], v[72:75]
	v_mfma_f32_16x16x32_bf16 v[60:63], v[36:39], v[204:207], v[60:63]
	v_mfma_f32_16x16x32_bf16 v[56:59], v[44:47], v[204:207], v[56:59]
	v_mfma_f32_16x16x32_bf16 v[28:31], v[36:39], v[212:215], v[28:31]
	v_mfma_f32_16x16x32_bf16 v[24:27], v[44:47], v[212:215], v[24:27]
	v_mfma_f32_16x16x32_bf16 v[12:15], v[36:39], v[220:223], v[12:15]
	v_mfma_f32_16x16x32_bf16 v[8:11], v[44:47], v[220:223], v[8:11]
	s_setprio 1
	s_setprio 0
	v_mfma_f32_16x16x32_bf16 v[20:23], v[144:147], v[208:211], v[20:23]
	v_mfma_f32_16x16x32_bf16 v[16:19], v[152:155], v[208:211], v[16:19]
	v_mfma_f32_16x16x32_bf16 v[4:7], v[144:147], v[216:219], v[4:7]
	v_mfma_f32_16x16x32_bf16 v[0:3], v[152:155], v[216:219], v[0:3]
	v_mfma_f32_16x16x32_bf16 v[32:35], v[144:147], v[192:195], v[68:71]
	v_mfma_f32_16x16x32_bf16 v[36:39], v[152:155], v[192:195], v[64:67]
	v_mfma_f32_16x16x32_bf16 v[40:43], v[144:147], v[200:203], v[52:55]
	v_mfma_f32_16x16x32_bf16 v[44:47], v[152:155], v[200:203], v[48:51]
	v_mfma_f32_16x16x32_bf16 v[20:23], v[148:151], v[212:215], v[20:23]
	v_mfma_f32_16x16x32_bf16 v[16:19], v[156:159], v[212:215], v[16:19]
	v_mfma_f32_16x16x32_bf16 v[4:7], v[148:151], v[220:223], v[4:7]
	v_mfma_f32_16x16x32_bf16 v[0:3], v[156:159], v[220:223], v[0:3]
	v_mfma_f32_16x16x32_bf16 v[32:35], v[148:151], v[196:199], v[32:35]
	v_mfma_f32_16x16x32_bf16 v[36:39], v[156:159], v[196:199], v[36:39]
	v_mfma_f32_16x16x32_bf16 v[40:43], v[148:151], v[204:207], v[40:43]
	v_mfma_f32_16x16x32_bf16 v[44:47], v[156:159], v[204:207], v[44:47]
	s_setprio 1
	s_barrier
	s_add_i32 s49, 0, 0x18000
	s_add_i32 s51, 0, 0x1c000
	v_add_u32_e32 v68, s49, v183
	v_add_u32_e32 v156, s51, v183
	ds_read_b128 v[48:51], v68
	ds_read_b128 v[52:55], v68 offset:1024
	ds_read_b128 v[64:67], v68 offset:2048
	ds_read_b128 v[68:71], v68 offset:3072
	ds_read_b128 v[144:147], v156
	ds_read_b128 v[148:151], v156 offset:1024
	ds_read_b128 v[152:155], v156 offset:2048
	ds_read_b128 v[156:159], v156 offset:3072
	s_add_u32 s34, s56, 0x40000
	s_addc_u32 s35, s57, 0
	s_mov_b32 m0, s63
	v_lshl_add_u64 v[230:231], s[34:35], 0, v[160:161]
	ds_read_b128 v[192:195], v188 offset:32768
	ds_read_b128 v[196:199], v188 offset:33792
	ds_read_b128 v[200:203], v188 offset:34816
	ds_read_b128 v[204:207], v188 offset:35840
	ds_read_b128 v[208:211], v188 offset:36864
	ds_read_b128 v[212:215], v188 offset:37888
	ds_read_b128 v[216:219], v188 offset:38912
	ds_read_b128 v[220:223], v188 offset:39936
	global_load_lds_dwordx4 v[230:231], off
	v_lshl_add_u64 v[230:231], s[34:35], 0, v[164:165]
	s_mov_b32 m0, s64
	s_nop 0
	global_load_lds_dwordx4 v[230:231], off
	s_waitcnt vmcnt(8)
	s_waitcnt lgkmcnt(0)
	s_barrier
	s_setprio 0
	s_waitcnt lgkmcnt(0)
	v_mfma_f32_16x16x32_bf16 v[140:143], v[48:51], v[192:195], v[140:143]
	v_mfma_f32_16x16x32_bf16 v[136:139], v[64:67], v[192:195], v[136:139]
	v_mfma_f32_16x16x32_bf16 v[124:127], v[48:51], v[200:203], v[124:127]
	v_mfma_f32_16x16x32_bf16 v[120:123], v[64:67], v[200:203], v[120:123]
	v_mfma_f32_16x16x32_bf16 v[108:111], v[48:51], v[208:211], v[108:111]
	v_mfma_f32_16x16x32_bf16 v[104:107], v[64:67], v[208:211], v[104:107]
	v_mfma_f32_16x16x32_bf16 v[92:95], v[48:51], v[216:219], v[92:95]
	v_mfma_f32_16x16x32_bf16 v[88:91], v[64:67], v[216:219], v[88:91]
	v_mfma_f32_16x16x32_bf16 v[140:143], v[52:55], v[196:199], v[140:143]
	v_mfma_f32_16x16x32_bf16 v[136:139], v[68:71], v[196:199], v[136:139]
	v_mfma_f32_16x16x32_bf16 v[124:127], v[52:55], v[204:207], v[124:127]
	v_mfma_f32_16x16x32_bf16 v[120:123], v[68:71], v[204:207], v[120:123]
	v_mfma_f32_16x16x32_bf16 v[108:111], v[52:55], v[212:215], v[108:111]
	v_mfma_f32_16x16x32_bf16 v[104:107], v[68:71], v[212:215], v[104:107]
	v_mfma_f32_16x16x32_bf16 v[92:95], v[52:55], v[220:223], v[92:95]
	v_mfma_f32_16x16x32_bf16 v[88:91], v[68:71], v[220:223], v[88:91]
	s_setprio 1
	s_setprio 0
	v_mfma_f32_16x16x32_bf16 v[132:135], v[144:147], v[192:195], v[132:135]
	v_mfma_f32_16x16x32_bf16 v[128:131], v[152:155], v[192:195], v[128:131]
	v_mfma_f32_16x16x32_bf16 v[116:119], v[144:147], v[200:203], v[116:119]
	v_mfma_f32_16x16x32_bf16 v[112:115], v[152:155], v[200:203], v[112:115]
	v_mfma_f32_16x16x32_bf16 v[100:103], v[144:147], v[208:211], v[100:103]
	v_mfma_f32_16x16x32_bf16 v[96:99], v[152:155], v[208:211], v[96:99]
	v_mfma_f32_16x16x32_bf16 v[84:87], v[144:147], v[216:219], v[84:87]
	v_mfma_f32_16x16x32_bf16 v[80:83], v[152:155], v[216:219], v[80:83]
	v_mfma_f32_16x16x32_bf16 v[132:135], v[148:151], v[196:199], v[132:135]
	v_mfma_f32_16x16x32_bf16 v[128:131], v[156:159], v[196:199], v[128:131]
	v_mfma_f32_16x16x32_bf16 v[116:119], v[148:151], v[204:207], v[116:119]
	v_mfma_f32_16x16x32_bf16 v[112:115], v[156:159], v[204:207], v[112:115]
	v_mfma_f32_16x16x32_bf16 v[100:103], v[148:151], v[212:215], v[100:103]
	v_mfma_f32_16x16x32_bf16 v[96:99], v[156:159], v[212:215], v[96:99]
	v_mfma_f32_16x16x32_bf16 v[84:87], v[148:151], v[220:223], v[84:87]
	v_mfma_f32_16x16x32_bf16 v[80:83], v[156:159], v[220:223], v[80:83]
	s_setprio 1
	s_barrier
	v_lshl_add_u64 v[252:253], v[226:227], 0, s[46:47]
	s_mov_b32 m0, s78
	s_nop 0
	global_load_lds_dwordx4 v[252:253], off
	v_lshl_add_u64 v[252:253], v[228:229], 0, s[46:47]
	s_mov_b32 m0, s79
	s_nop 0
	global_load_lds_dwordx4 v[252:253], off
	s_add_i32 s34, s49, s60
	v_lshl_add_u64 v[180:181], v[180:181], 0, s[46:47]
	s_mov_b32 m0, s34
	ds_read_b128 v[192:195], v188 offset:49152
	ds_read_b128 v[196:199], v188 offset:50176
	ds_read_b128 v[200:203], v188 offset:51200
	ds_read_b128 v[204:207], v188 offset:52224
	ds_read_b128 v[208:211], v188 offset:53248
	ds_read_b128 v[212:215], v188 offset:54272
	ds_read_b128 v[216:219], v188 offset:55296
	ds_read_b128 v[220:223], v188 offset:56320
	global_load_lds_dwordx4 v[180:181], off
	s_add_i32 m0, s34, 0x2000
	s_add_u32 s8, s8, 0x40080
	v_lshl_add_u64 v[180:181], v[224:225], 0, s[46:47]
	s_addc_u32 s9, s9, 0
	s_add_i32 s34, s51, s60
	global_load_lds_dwordx4 v[180:181], off
	v_lshl_add_u64 v[180:181], s[8:9], 0, v[162:163]
	s_mov_b32 m0, s34
	s_nop 0
	global_load_lds_dwordx4 v[180:181], off
	v_lshl_add_u64 v[180:181], s[8:9], 0, v[166:167]
	s_add_i32 m0, s34, 0x2000
	s_nop 0
	global_load_lds_dwordx4 v[180:181], off
	v_lshl_add_u64 v[180:181], v[226:227], 0, s[46:47]
	v_lshl_add_u64 v[180:181], v[228:229], 0, s[46:47]
	s_waitcnt vmcnt(8)
	s_waitcnt lgkmcnt(0)
	s_barrier
	s_setprio 0
	s_waitcnt lgkmcnt(0)
	v_mfma_f32_16x16x32_bf16 v[76:79], v[48:51], v[192:195], v[76:79]
	v_mfma_f32_16x16x32_bf16 v[72:75], v[64:67], v[192:195], v[72:75]
	v_mfma_f32_16x16x32_bf16 v[60:63], v[48:51], v[200:203], v[60:63]
	v_mfma_f32_16x16x32_bf16 v[56:59], v[64:67], v[200:203], v[56:59]
	v_mfma_f32_16x16x32_bf16 v[28:31], v[48:51], v[208:211], v[28:31]
	v_mfma_f32_16x16x32_bf16 v[24:27], v[64:67], v[208:211], v[24:27]
	v_mfma_f32_16x16x32_bf16 v[12:15], v[48:51], v[216:219], v[12:15]
	v_mfma_f32_16x16x32_bf16 v[8:11], v[64:67], v[216:219], v[8:11]
	v_mfma_f32_16x16x32_bf16 v[76:79], v[52:55], v[196:199], v[76:79]
	v_mfma_f32_16x16x32_bf16 v[72:75], v[68:71], v[196:199], v[72:75]
	v_mfma_f32_16x16x32_bf16 v[60:63], v[52:55], v[204:207], v[60:63]
	v_mfma_f32_16x16x32_bf16 v[56:59], v[68:71], v[204:207], v[56:59]
	v_mfma_f32_16x16x32_bf16 v[28:31], v[52:55], v[212:215], v[28:31]
	v_mfma_f32_16x16x32_bf16 v[24:27], v[68:71], v[212:215], v[24:27]
	v_mfma_f32_16x16x32_bf16 v[12:15], v[52:55], v[220:223], v[12:15]
	v_mfma_f32_16x16x32_bf16 v[8:11], v[68:71], v[220:223], v[8:11]
	s_setprio 1
	s_setprio 0
	v_mfma_f32_16x16x32_bf16 v[32:35], v[144:147], v[192:195], v[32:35]
	v_mfma_f32_16x16x32_bf16 v[68:71], v[148:151], v[196:199], v[32:35]
	v_mfma_f32_16x16x32_bf16 v[32:35], v[152:155], v[192:195], v[36:39]
	v_mfma_f32_16x16x32_bf16 v[64:67], v[156:159], v[196:199], v[32:35]
	v_mfma_f32_16x16x32_bf16 v[32:35], v[144:147], v[200:203], v[40:43]
	v_mfma_f32_16x16x32_bf16 v[52:55], v[148:151], v[204:207], v[32:35]
	v_mfma_f32_16x16x32_bf16 v[32:35], v[152:155], v[200:203], v[44:47]
	v_mfma_f32_16x16x32_bf16 v[20:23], v[144:147], v[208:211], v[20:23]
	v_mfma_f32_16x16x32_bf16 v[16:19], v[152:155], v[208:211], v[16:19]
	v_mfma_f32_16x16x32_bf16 v[4:7], v[144:147], v[216:219], v[4:7]
	v_mfma_f32_16x16x32_bf16 v[0:3], v[152:155], v[216:219], v[0:3]
	v_mfma_f32_16x16x32_bf16 v[48:51], v[156:159], v[204:207], v[32:35]
	v_mfma_f32_16x16x32_bf16 v[20:23], v[148:151], v[212:215], v[20:23]
	v_mfma_f32_16x16x32_bf16 v[16:19], v[156:159], v[212:215], v[16:19]
	v_mfma_f32_16x16x32_bf16 v[4:7], v[148:151], v[220:223], v[4:7]
	v_mfma_f32_16x16x32_bf16 v[0:3], v[156:159], v[220:223], v[0:3]
	s_setprio 1
	s_barrier
	s_add_i32 s33, s33, 2
	s_add_u32 s6, s6, 0x100
	s_addc_u32 s7, s7, 0
	s_add_u32 s25, s25, 0x100
	s_addc_u32 s30, s30, 0
	s_cmp_gt_u32 s33, 13
	s_cbranch_scc0 .LBB5_625
	s_nop 0
	s_nop 0
	s_nop 0
	s_nop 0
	s_nop 0
	s_nop 0
	s_nop 0
	s_nop 0
	s_setprio 0
	s_nop 0
	s_nop 0
	s_nop 0
	s_nop 0
	s_nop 0
	s_nop 0
	s_nop 0
	s_nop 0
	s_nop 0
	s_nop 0
	s_nop 0
	s_nop 0
	s_nop 0
	s_and_b64 vcc, exec, s[42:43]
	s_cbranch_vccz .LBB5_628
	s_barrier

.Lskw_P8:
	s_waitcnt lgkmcnt(0)
	s_barrier
	s_setprio 0
	s_waitcnt lgkmcnt(0)
	v_mfma_f32_16x16x32_bf16 v[124:127], v[128:131], v[176:179], v[124:127]
	v_mfma_f32_16x16x32_bf16 v[120:123], v[136:139], v[176:179], v[120:123]
	v_mfma_f32_16x16x32_bf16 v[108:111], v[128:131], v[194:197], v[108:111]
	v_mfma_f32_16x16x32_bf16 v[104:107], v[136:139], v[194:197], v[104:107]
	v_mfma_f32_16x16x32_bf16 v[92:95], v[128:131], v[202:205], v[92:95]
	v_mfma_f32_16x16x32_bf16 v[88:91], v[136:139], v[202:205], v[88:91]
	v_mfma_f32_16x16x32_bf16 v[76:79], v[128:131], v[210:213], v[76:79]
	v_mfma_f32_16x16x32_bf16 v[72:75], v[136:139], v[210:213], v[72:75]
	v_mfma_f32_16x16x32_bf16 v[124:127], v[132:135], v[180:183], v[124:127]
	v_mfma_f32_16x16x32_bf16 v[120:123], v[140:143], v[180:183], v[120:123]
	v_mfma_f32_16x16x32_bf16 v[108:111], v[132:135], v[198:201], v[108:111]
	v_mfma_f32_16x16x32_bf16 v[104:107], v[140:143], v[198:201], v[104:107]
	v_mfma_f32_16x16x32_bf16 v[92:95], v[132:135], v[206:209], v[92:95]
	v_mfma_f32_16x16x32_bf16 v[88:91], v[140:143], v[206:209], v[88:91]
	v_mfma_f32_16x16x32_bf16 v[76:79], v[132:135], v[214:217], v[76:79]
	v_mfma_f32_16x16x32_bf16 v[72:75], v[140:143], v[214:217], v[72:75]
	s_setprio 1
	s_setprio 0
	v_mfma_f32_16x16x32_bf16 v[116:119], v[144:147], v[176:179], v[116:119]
	v_mfma_f32_16x16x32_bf16 v[112:115], v[168:171], v[176:179], v[112:115]
	v_mfma_f32_16x16x32_bf16 v[100:103], v[144:147], v[194:197], v[100:103]
	v_mfma_f32_16x16x32_bf16 v[96:99], v[168:171], v[194:197], v[96:99]
	v_mfma_f32_16x16x32_bf16 v[84:87], v[144:147], v[202:205], v[84:87]
	v_mfma_f32_16x16x32_bf16 v[80:83], v[168:171], v[202:205], v[80:83]
	v_mfma_f32_16x16x32_bf16 v[68:71], v[144:147], v[210:213], v[68:71]
	v_mfma_f32_16x16x32_bf16 v[64:67], v[168:171], v[210:213], v[64:67]
	v_mfma_f32_16x16x32_bf16 v[116:119], v[148:151], v[180:183], v[116:119]
	v_mfma_f32_16x16x32_bf16 v[112:115], v[172:175], v[180:183], v[112:115]
	v_mfma_f32_16x16x32_bf16 v[100:103], v[148:151], v[198:201], v[100:103]
	v_mfma_f32_16x16x32_bf16 v[96:99], v[172:175], v[198:201], v[96:99]
	v_mfma_f32_16x16x32_bf16 v[84:87], v[148:151], v[206:209], v[84:87]
	v_mfma_f32_16x16x32_bf16 v[80:83], v[172:175], v[206:209], v[80:83]
	v_mfma_f32_16x16x32_bf16 v[68:71], v[148:151], v[214:217], v[68:71]
	v_mfma_f32_16x16x32_bf16 v[64:67], v[172:175], v[214:217], v[64:67]
	s_setprio 1
	s_barrier
	v_lshl_add_u64 v[252:253], s[42:43], 0, v[152:153]
	s_mov_b32 m0, s34
	s_nop 0
	global_load_lds_dwordx4 v[252:253], off
	v_lshl_add_u64 v[252:253], s[42:43], 0, v[156:157]
	s_mov_b32 m0, s35
	s_nop 0
	global_load_lds_dwordx4 v[252:253], off
	s_add_i32 s58, s51, s33
	v_lshl_add_u64 v[184:185], s[40:41], 0, v[154:155]
	s_mov_b32 m0, s58
	ds_read_b128 v[176:179], v193 offset:16384
	ds_read_b128 v[180:183], v193 offset:17408
	ds_read_b128 v[194:197], v193 offset:18432
	ds_read_b128 v[198:201], v193 offset:19456
	ds_read_b128 v[202:205], v193 offset:20480
	ds_read_b128 v[206:209], v193 offset:21504
	ds_read_b128 v[210:213], v193 offset:22528
	ds_read_b128 v[214:217], v193 offset:23552
	global_load_lds_dwordx4 v[184:185], off
	s_add_i32 m0, s58, 0x2000
	s_add_u32 s58, s40, 0x40000
	v_lshl_add_u64 v[218:219], s[40:41], 0, v[158:159]
	s_addc_u32 s59, s41, 0
	s_add_i32 s60, s52, s33
	global_load_lds_dwordx4 v[218:219], off
	v_lshl_add_u64 v[220:221], s[58:59], 0, v[154:155]
	s_mov_b32 m0, s60
	v_lshl_add_u64 v[222:223], s[42:43], 0, v[156:157]
	global_load_lds_dwordx4 v[220:221], off
	v_lshl_add_u64 v[220:221], s[58:59], 0, v[158:159]
	s_add_i32 m0, s60, 0x2000
	s_nop 0
	global_load_lds_dwordx4 v[220:221], off
	v_lshl_add_u64 v[220:221], s[42:43], 0, v[152:153]
	s_waitcnt vmcnt(8)
	s_waitcnt lgkmcnt(0)
	s_barrier
	s_setprio 0
	s_waitcnt lgkmcnt(0)
	v_mfma_f32_16x16x32_bf16 v[60:63], v[128:131], v[176:179], v[60:63]
	v_mfma_f32_16x16x32_bf16 v[56:59], v[136:139], v[176:179], v[56:59]
	v_mfma_f32_16x16x32_bf16 v[44:47], v[128:131], v[194:197], v[44:47]
	v_mfma_f32_16x16x32_bf16 v[40:43], v[136:139], v[194:197], v[40:43]
	v_mfma_f32_16x16x32_bf16 v[28:31], v[128:131], v[202:205], v[28:31]
	v_mfma_f32_16x16x32_bf16 v[24:27], v[136:139], v[202:205], v[24:27]
	v_mfma_f32_16x16x32_bf16 v[12:15], v[128:131], v[210:213], v[12:15]
	v_mfma_f32_16x16x32_bf16 v[8:11], v[136:139], v[210:213], v[8:11]
	v_mfma_f32_16x16x32_bf16 v[60:63], v[132:135], v[180:183], v[60:63]
	v_mfma_f32_16x16x32_bf16 v[56:59], v[140:143], v[180:183], v[56:59]
	v_mfma_f32_16x16x32_bf16 v[44:47], v[132:135], v[198:201], v[44:47]
	v_mfma_f32_16x16x32_bf16 v[40:43], v[140:143], v[198:201], v[40:43]
	v_mfma_f32_16x16x32_bf16 v[28:31], v[132:135], v[206:209], v[28:31]
	v_mfma_f32_16x16x32_bf16 v[24:27], v[140:143], v[206:209], v[24:27]
	v_mfma_f32_16x16x32_bf16 v[12:15], v[132:135], v[214:217], v[12:15]
	v_mfma_f32_16x16x32_bf16 v[8:11], v[140:143], v[214:217], v[8:11]
	s_setprio 1
	s_setprio 0
	v_mfma_f32_16x16x32_bf16 v[52:55], v[144:147], v[176:179], v[52:55]
	v_mfma_f32_16x16x32_bf16 v[48:51], v[168:171], v[176:179], v[48:51]
	v_mfma_f32_16x16x32_bf16 v[36:39], v[144:147], v[194:197], v[36:39]
	v_mfma_f32_16x16x32_bf16 v[32:35], v[168:171], v[194:197], v[32:35]
	v_mfma_f32_16x16x32_bf16 v[20:23], v[144:147], v[202:205], v[20:23]
	v_mfma_f32_16x16x32_bf16 v[16:19], v[168:171], v[202:205], v[16:19]
	v_mfma_f32_16x16x32_bf16 v[4:7], v[144:147], v[210:213], v[4:7]
	v_mfma_f32_16x16x32_bf16 v[0:3], v[168:171], v[210:213], v[0:3]
	v_mfma_f32_16x16x32_bf16 v[52:55], v[148:151], v[180:183], v[52:55]
	v_mfma_f32_16x16x32_bf16 v[48:51], v[172:175], v[180:183], v[48:51]
	v_mfma_f32_16x16x32_bf16 v[36:39], v[148:151], v[198:201], v[36:39]
	v_mfma_f32_16x16x32_bf16 v[32:35], v[172:175], v[198:201], v[32:35]
	v_mfma_f32_16x16x32_bf16 v[20:23], v[148:151], v[206:209], v[20:23]
	v_mfma_f32_16x16x32_bf16 v[16:19], v[172:175], v[206:209], v[16:19]
	v_mfma_f32_16x16x32_bf16 v[4:7], v[148:151], v[214:217], v[4:7]
	v_mfma_f32_16x16x32_bf16 v[0:3], v[172:175], v[214:217], v[0:3]
	s_setprio 1
	s_barrier
	s_add_i32 s58, 0, 0x18000
	s_add_i32 s59, 0, 0x1c000
	v_add_u32_e32 v140, s58, v187
	v_add_u32_e32 v172, s59, v187
	ds_read_b128 v[128:131], v140
	ds_read_b128 v[132:135], v140 offset:1024
	ds_read_b128 v[136:139], v140 offset:2048
	ds_read_b128 v[140:143], v140 offset:3072
	ds_read_b128 v[144:147], v172
	ds_read_b128 v[148:151], v172 offset:1024
	ds_read_b128 v[168:171], v172 offset:2048
	ds_read_b128 v[172:175], v172 offset:3072
	s_add_u32 s42, s42, 0x40000
	s_addc_u32 s43, s43, 0
	s_mov_b32 m0, s44
	v_lshl_add_u64 v[224:225], s[42:43], 0, v[152:153]
	ds_read_b128 v[176:179], v193 offset:32768
	ds_read_b128 v[180:183], v193 offset:33792
	ds_read_b128 v[194:197], v193 offset:34816
	ds_read_b128 v[198:201], v193 offset:35840
	ds_read_b128 v[202:205], v193 offset:36864
	ds_read_b128 v[206:209], v193 offset:37888
	ds_read_b128 v[210:213], v193 offset:38912
	ds_read_b128 v[214:217], v193 offset:39936
	global_load_lds_dwordx4 v[224:225], off
	v_lshl_add_u64 v[224:225], s[42:43], 0, v[156:157]
	s_mov_b32 m0, s45
	s_nop 0
	global_load_lds_dwordx4 v[224:225], off
	s_waitcnt vmcnt(8)
	s_waitcnt lgkmcnt(0)
	s_barrier
	s_setprio 0
	s_waitcnt lgkmcnt(0)
	v_mfma_f32_16x16x32_bf16 v[124:127], v[128:131], v[176:179], v[124:127]
	v_mfma_f32_16x16x32_bf16 v[120:123], v[136:139], v[176:179], v[120:123]
	v_mfma_f32_16x16x32_bf16 v[108:111], v[128:131], v[194:197], v[108:111]
	v_mfma_f32_16x16x32_bf16 v[104:107], v[136:139], v[194:197], v[104:107]
	v_mfma_f32_16x16x32_bf16 v[92:95], v[128:131], v[202:205], v[92:95]
	v_mfma_f32_16x16x32_bf16 v[88:91], v[136:139], v[202:205], v[88:91]
	v_mfma_f32_16x16x32_bf16 v[76:79], v[128:131], v[210:213], v[76:79]
	v_mfma_f32_16x16x32_bf16 v[72:75], v[136:139], v[210:213], v[72:75]
	v_mfma_f32_16x16x32_bf16 v[124:127], v[132:135], v[180:183], v[124:127]
	v_mfma_f32_16x16x32_bf16 v[120:123], v[140:143], v[180:183], v[120:123]
	v_mfma_f32_16x16x32_bf16 v[108:111], v[132:135], v[198:201], v[108:111]
	v_mfma_f32_16x16x32_bf16 v[104:107], v[140:143], v[198:201], v[104:107]
	v_mfma_f32_16x16x32_bf16 v[92:95], v[132:135], v[206:209], v[92:95]
	v_mfma_f32_16x16x32_bf16 v[88:91], v[140:143], v[206:209], v[88:91]
	v_mfma_f32_16x16x32_bf16 v[76:79], v[132:135], v[214:217], v[76:79]
	v_mfma_f32_16x16x32_bf16 v[72:75], v[140:143], v[214:217], v[72:75]
	s_setprio 1
	s_setprio 0
	v_mfma_f32_16x16x32_bf16 v[116:119], v[144:147], v[176:179], v[116:119]
	v_mfma_f32_16x16x32_bf16 v[112:115], v[168:171], v[176:179], v[112:115]
	v_mfma_f32_16x16x32_bf16 v[100:103], v[144:147], v[194:197], v[100:103]
	v_mfma_f32_16x16x32_bf16 v[96:99], v[168:171], v[194:197], v[96:99]
	v_mfma_f32_16x16x32_bf16 v[84:87], v[144:147], v[202:205], v[84:87]
	v_mfma_f32_16x16x32_bf16 v[80:83], v[168:171], v[202:205], v[80:83]
	v_mfma_f32_16x16x32_bf16 v[68:71], v[144:147], v[210:213], v[68:71]
	v_mfma_f32_16x16x32_bf16 v[64:67], v[168:171], v[210:213], v[64:67]
	v_mfma_f32_16x16x32_bf16 v[116:119], v[148:151], v[180:183], v[116:119]
	v_mfma_f32_16x16x32_bf16 v[112:115], v[172:175], v[180:183], v[112:115]
	v_mfma_f32_16x16x32_bf16 v[100:103], v[148:151], v[198:201], v[100:103]
	v_mfma_f32_16x16x32_bf16 v[96:99], v[172:175], v[198:201], v[96:99]
	v_mfma_f32_16x16x32_bf16 v[84:87], v[148:151], v[206:209], v[84:87]
	v_mfma_f32_16x16x32_bf16 v[80:83], v[172:175], v[206:209], v[80:83]
	v_mfma_f32_16x16x32_bf16 v[68:71], v[148:151], v[214:217], v[68:71]
	v_mfma_f32_16x16x32_bf16 v[64:67], v[172:175], v[214:217], v[64:67]
	s_setprio 1
	s_barrier
	v_lshl_add_u64 v[252:253], v[220:221], 0, s[18:19]
	s_mov_b32 m0, s49
	s_nop 0
	global_load_lds_dwordx4 v[252:253], off
	v_lshl_add_u64 v[252:253], v[222:223], 0, s[18:19]
	s_mov_b32 m0, s50
	s_nop 0
	global_load_lds_dwordx4 v[252:253], off
	s_add_i32 s42, s58, s33
	v_lshl_add_u64 v[184:185], v[184:185], 0, s[18:19]
	s_mov_b32 m0, s42
	ds_read_b128 v[176:179], v193 offset:49152
	ds_read_b128 v[180:183], v193 offset:50176
	ds_read_b128 v[194:197], v193 offset:51200
	ds_read_b128 v[198:201], v193 offset:52224
	ds_read_b128 v[202:205], v193 offset:53248
	ds_read_b128 v[206:209], v193 offset:54272
	ds_read_b128 v[210:213], v193 offset:55296
	ds_read_b128 v[214:217], v193 offset:56320
	global_load_lds_dwordx4 v[184:185], off
	s_add_i32 m0, s42, 0x2000
	s_add_u32 s40, s40, 0x40080
	v_lshl_add_u64 v[184:185], v[218:219], 0, s[18:19]
	s_addc_u32 s41, s41, 0
	s_add_i32 s42, s59, s33
	global_load_lds_dwordx4 v[184:185], off
	v_lshl_add_u64 v[184:185], s[40:41], 0, v[154:155]
	s_mov_b32 m0, s42
	s_nop 0
	global_load_lds_dwordx4 v[184:185], off
	v_lshl_add_u64 v[184:185], s[40:41], 0, v[158:159]
	s_add_i32 m0, s42, 0x2000
	s_nop 0
	global_load_lds_dwordx4 v[184:185], off
	v_lshl_add_u64 v[184:185], v[220:221], 0, s[18:19]
	v_lshl_add_u64 v[184:185], v[222:223], 0, s[18:19]
	s_waitcnt vmcnt(8)
	s_waitcnt lgkmcnt(0)
	s_barrier
	s_setprio 0
	s_waitcnt lgkmcnt(0)
	v_mfma_f32_16x16x32_bf16 v[60:63], v[128:131], v[176:179], v[60:63]
	v_mfma_f32_16x16x32_bf16 v[56:59], v[136:139], v[176:179], v[56:59]
	v_mfma_f32_16x16x32_bf16 v[44:47], v[128:131], v[194:197], v[44:47]
	v_mfma_f32_16x16x32_bf16 v[40:43], v[136:139], v[194:197], v[40:43]
	v_mfma_f32_16x16x32_bf16 v[28:31], v[128:131], v[202:205], v[28:31]
	v_mfma_f32_16x16x32_bf16 v[24:27], v[136:139], v[202:205], v[24:27]
	v_mfma_f32_16x16x32_bf16 v[12:15], v[128:131], v[210:213], v[12:15]
	v_mfma_f32_16x16x32_bf16 v[8:11], v[136:139], v[210:213], v[8:11]
	v_mfma_f32_16x16x32_bf16 v[60:63], v[132:135], v[180:183], v[60:63]
	v_mfma_f32_16x16x32_bf16 v[56:59], v[140:143], v[180:183], v[56:59]
	v_mfma_f32_16x16x32_bf16 v[44:47], v[132:135], v[198:201], v[44:47]
	v_mfma_f32_16x16x32_bf16 v[40:43], v[140:143], v[198:201], v[40:43]
	v_mfma_f32_16x16x32_bf16 v[28:31], v[132:135], v[206:209], v[28:31]
	v_mfma_f32_16x16x32_bf16 v[24:27], v[140:143], v[206:209], v[24:27]
	v_mfma_f32_16x16x32_bf16 v[12:15], v[132:135], v[214:217], v[12:15]
	v_mfma_f32_16x16x32_bf16 v[8:11], v[140:143], v[214:217], v[8:11]
	s_setprio 1
	s_setprio 0
	v_mfma_f32_16x16x32_bf16 v[52:55], v[144:147], v[176:179], v[52:55]
	v_mfma_f32_16x16x32_bf16 v[48:51], v[168:171], v[176:179], v[48:51]
	v_mfma_f32_16x16x32_bf16 v[36:39], v[144:147], v[194:197], v[36:39]
	v_mfma_f32_16x16x32_bf16 v[32:35], v[168:171], v[194:197], v[32:35]
	v_mfma_f32_16x16x32_bf16 v[20:23], v[144:147], v[202:205], v[20:23]
	v_mfma_f32_16x16x32_bf16 v[16:19], v[168:171], v[202:205], v[16:19]
	v_mfma_f32_16x16x32_bf16 v[4:7], v[144:147], v[210:213], v[4:7]
	v_mfma_f32_16x16x32_bf16 v[0:3], v[168:171], v[210:213], v[0:3]
	v_mfma_f32_16x16x32_bf16 v[52:55], v[148:151], v[180:183], v[52:55]
	v_mfma_f32_16x16x32_bf16 v[48:51], v[172:175], v[180:183], v[48:51]
	v_mfma_f32_16x16x32_bf16 v[36:39], v[148:151], v[198:201], v[36:39]
	v_mfma_f32_16x16x32_bf16 v[32:35], v[172:175], v[198:201], v[32:35]
	v_mfma_f32_16x16x32_bf16 v[20:23], v[148:151], v[206:209], v[20:23]
	v_mfma_f32_16x16x32_bf16 v[16:19], v[172:175], v[206:209], v[16:19]
	v_mfma_f32_16x16x32_bf16 v[4:7], v[148:151], v[214:217], v[4:7]
	v_mfma_f32_16x16x32_bf16 v[0:3], v[172:175], v[214:217], v[0:3]
	s_setprio 1
	s_barrier
	s_add_i32 s57, s57, 2
	s_add_u32 s38, s38, 0x100
	s_addc_u32 s39, s39, 0
	s_add_u32 s55, s55, 0x100
	s_addc_u32 s56, s56, 0
	s_cmp_gt_u32 s57, 13
	s_cbranch_scc0 .LBB5_969
	s_nop 0
	s_nop 0
	s_nop 0
	s_nop 0
	s_nop 0
	s_nop 0
	s_nop 0
	s_nop 0
	s_setprio 0
	s_nop 0
	s_nop 0
	s_nop 0
	s_nop 0
	s_nop 0
	s_nop 0
	s_nop 0
	s_nop 0
	s_nop 0
	s_nop 0
	s_nop 0
	s_nop 0
	s_nop 0
	s_and_b64 vcc, exec, s[16:17]
	s_cbranch_vccz .LBB5_972
	s_barrier
